# hand-written staged epilogue for the NQ and SZ tiles of NA G1 (ph13)
# speedup vs baseline: 1.0359x; 1.0100x over previous
.Lgm_ph13_loop:
	s_waitcnt lgkmcnt(1)
	v_mfma_f32_32x32x16_bf16 v[82:97], v[240:243], v[252:255], v[82:97]
	ds_read_b128 v[220:223], v210 offset:0
	s_add_u32 m0, s81, 0x5000
	s_nop 0
	global_load_lds_dwordx4 v202, s[70:71]
	v_mfma_f32_32x32x16_bf16 v[66:81], v[236:239], v[252:255], v[66:81]
	ds_read_b128 v[232:235], v214 offset:0
	s_add_u32 m0, s82, 0x0
	s_nop 0
	global_load_lds_dwordx4 v207, s[72:73]
	v_mfma_f32_32x32x16_bf16 v[50:65], v[240:243], v[248:251], v[50:65]
	ds_read_b128 v[216:219], v210 offset:4096
	s_add_u32 m0, s82, 0x1000
	s_nop 0
	global_load_lds_dwordx4 v206, s[72:73]
	v_mfma_f32_32x32x16_bf16 v[34:49], v[236:239], v[248:251], v[34:49]
	ds_read_b128 v[228:231], v214 offset:4096
	s_add_u32 m0, s82, 0x2000
	s_nop 0
	global_load_lds_dwordx4 v205, s[72:73]
	s_waitcnt lgkmcnt(4)
	v_mfma_f32_32x32x16_bf16 v[18:33], v[240:243], v[244:247], v[18:33]
	ds_read_b128 v[224:227], v214 offset:8192
	v_mfma_f32_32x32x16_bf16 v[2:17], v[236:239], v[244:247], v[2:17]
	s_add_u32 m0, s82, 0x3000
	s_nop 0
	global_load_lds_dwordx4 v204, s[72:73]
	s_waitcnt lgkmcnt(1)
	v_mfma_f32_32x32x16_bf16 v[82:97], v[220:223], v[232:235], v[82:97]
	ds_read_b128 v[240:243], v209 offset:0
	v_mfma_f32_32x32x16_bf16 v[66:81], v[216:219], v[232:235], v[66:81]
	ds_read_b128 v[252:255], v213 offset:0
	v_mfma_f32_32x32x16_bf16 v[50:65], v[220:223], v[228:231], v[50:65]
	ds_read_b128 v[236:239], v209 offset:4096
	v_mfma_f32_32x32x16_bf16 v[34:49], v[216:219], v[228:231], v[34:49]
	ds_read_b128 v[248:251], v213 offset:4096
	s_waitcnt lgkmcnt(4)
	v_mfma_f32_32x32x16_bf16 v[18:33], v[220:223], v[224:227], v[18:33]
	ds_read_b128 v[244:247], v213 offset:8192
	v_mfma_f32_32x32x16_bf16 v[2:17], v[216:219], v[224:227], v[2:17]
	s_waitcnt lgkmcnt(1)
	v_mfma_f32_32x32x16_bf16 v[82:97], v[240:243], v[252:255], v[82:97]
	ds_read_b128 v[220:223], v208 offset:0
	s_add_u32 s83, s79, s78
	s_add_u32 s83, s83, 2
	s_and_b32 s83, s83, 15
	v_mfma_f32_32x32x16_bf16 v[66:81], v[236:239], v[252:255], v[66:81]
	ds_read_b128 v[232:235], v212 offset:0
	s_lshl_b32 s83, s83, 7
	s_add_u32 s70, s66, s83
	v_mfma_f32_32x32x16_bf16 v[50:65], v[240:243], v[248:251], v[50:65]
	ds_read_b128 v[216:219], v208 offset:4096
	s_addc_u32 s71, s67, 0
	s_add_u32 s72, s68, s83
	v_mfma_f32_32x32x16_bf16 v[34:49], v[236:239], v[248:251], v[34:49]
	ds_read_b128 v[228:231], v212 offset:4096
	s_addc_u32 s73, s69, 0
	s_add_u32 s81, s80, 0x0
	s_add_u32 s82, s80, 0xc000
	s_waitcnt lgkmcnt(4)
	v_mfma_f32_32x32x16_bf16 v[18:33], v[240:243], v[244:247], v[18:33]
	ds_read_b128 v[224:227], v212 offset:8192
	v_mfma_f32_32x32x16_bf16 v[2:17], v[236:239], v[244:247], v[2:17]
	s_waitcnt vmcnt(0) lgkmcnt(0)
	s_barrier
	v_mfma_f32_32x32x16_bf16 v[82:97], v[220:223], v[232:235], v[82:97]
	s_add_u32 m0, s81, 0x0
	ds_read_b128 v[240:243], v211 offset:16384
	global_load_lds_dwordx4 v207, s[70:71]
	v_mfma_f32_32x32x16_bf16 v[66:81], v[216:219], v[232:235], v[66:81]
	s_add_u32 m0, s81, 0x1000
	ds_read_b128 v[252:255], v215 offset:24576
	global_load_lds_dwordx4 v206, s[70:71]
	v_mfma_f32_32x32x16_bf16 v[50:65], v[220:223], v[228:231], v[50:65]
	s_add_u32 m0, s81, 0x2000
	ds_read_b128 v[236:239], v211 offset:20480
	global_load_lds_dwordx4 v205, s[70:71]
	v_mfma_f32_32x32x16_bf16 v[34:49], v[216:219], v[228:231], v[34:49]
	s_add_u32 m0, s81, 0x3000
	ds_read_b128 v[248:251], v215 offset:28672
	global_load_lds_dwordx4 v204, s[70:71]
	v_mfma_f32_32x32x16_bf16 v[18:33], v[220:223], v[224:227], v[18:33]
	s_add_u32 m0, s81, 0x4000
	ds_read_b128 v[244:247], v215 offset:32768
	global_load_lds_dwordx4 v203, s[70:71]
	v_mfma_f32_32x32x16_bf16 v[2:17], v[216:219], v[224:227], v[2:17]
	s_waitcnt lgkmcnt(1)
	v_mfma_f32_32x32x16_bf16 v[82:97], v[240:243], v[252:255], v[82:97]
	ds_read_b128 v[220:223], v210 offset:16384
	s_add_u32 m0, s81, 0x5000
	s_nop 0
	global_load_lds_dwordx4 v202, s[70:71]
	v_mfma_f32_32x32x16_bf16 v[66:81], v[236:239], v[252:255], v[66:81]
	ds_read_b128 v[232:235], v214 offset:24576
	s_add_u32 m0, s82, 0x0
	s_nop 0
	global_load_lds_dwordx4 v207, s[72:73]
	v_mfma_f32_32x32x16_bf16 v[50:65], v[240:243], v[248:251], v[50:65]
	ds_read_b128 v[216:219], v210 offset:20480
	s_add_u32 m0, s82, 0x1000
	s_nop 0
	global_load_lds_dwordx4 v206, s[72:73]
	v_mfma_f32_32x32x16_bf16 v[34:49], v[236:239], v[248:251], v[34:49]
	ds_read_b128 v[228:231], v214 offset:28672
	s_add_u32 m0, s82, 0x2000
	s_nop 0
	global_load_lds_dwordx4 v205, s[72:73]
	s_waitcnt lgkmcnt(4)
	v_mfma_f32_32x32x16_bf16 v[18:33], v[240:243], v[244:247], v[18:33]
	ds_read_b128 v[224:227], v214 offset:32768
	v_mfma_f32_32x32x16_bf16 v[2:17], v[236:239], v[244:247], v[2:17]
	s_add_u32 m0, s82, 0x3000
	s_nop 0
	global_load_lds_dwordx4 v204, s[72:73]
	s_waitcnt lgkmcnt(1)
	v_mfma_f32_32x32x16_bf16 v[82:97], v[220:223], v[232:235], v[82:97]
	ds_read_b128 v[240:243], v209 offset:16384
	v_mfma_f32_32x32x16_bf16 v[66:81], v[216:219], v[232:235], v[66:81]
	ds_read_b128 v[252:255], v213 offset:24576
	v_mfma_f32_32x32x16_bf16 v[50:65], v[220:223], v[228:231], v[50:65]
	ds_read_b128 v[236:239], v209 offset:20480
	v_mfma_f32_32x32x16_bf16 v[34:49], v[216:219], v[228:231], v[34:49]
	ds_read_b128 v[248:251], v213 offset:28672
	s_waitcnt lgkmcnt(4)
	v_mfma_f32_32x32x16_bf16 v[18:33], v[220:223], v[224:227], v[18:33]
	ds_read_b128 v[244:247], v213 offset:32768
	v_mfma_f32_32x32x16_bf16 v[2:17], v[216:219], v[224:227], v[2:17]
	s_waitcnt lgkmcnt(1)
	v_mfma_f32_32x32x16_bf16 v[82:97], v[240:243], v[252:255], v[82:97]
	ds_read_b128 v[220:223], v208 offset:16384
	s_add_u32 s83, s79, s78
	s_add_u32 s83, s83, 3
	s_and_b32 s83, s83, 15
	v_mfma_f32_32x32x16_bf16 v[66:81], v[236:239], v[252:255], v[66:81]
	ds_read_b128 v[232:235], v212 offset:24576
	s_lshl_b32 s83, s83, 7
	s_add_u32 s70, s66, s83
	v_mfma_f32_32x32x16_bf16 v[50:65], v[240:243], v[248:251], v[50:65]
	ds_read_b128 v[216:219], v208 offset:20480
	s_addc_u32 s71, s67, 0
	s_add_u32 s72, s68, s83
	v_mfma_f32_32x32x16_bf16 v[34:49], v[236:239], v[248:251], v[34:49]
	ds_read_b128 v[228:231], v212 offset:28672
	s_addc_u32 s73, s69, 0
	s_add_u32 s81, s80, 0x6000
	s_add_u32 s82, s80, 0x10000
	s_waitcnt lgkmcnt(4)
	v_mfma_f32_32x32x16_bf16 v[18:33], v[240:243], v[244:247], v[18:33]
	ds_read_b128 v[224:227], v212 offset:32768
	v_mfma_f32_32x32x16_bf16 v[2:17], v[236:239], v[244:247], v[2:17]
	s_waitcnt vmcnt(0) lgkmcnt(0)
	s_barrier
	v_mfma_f32_32x32x16_bf16 v[82:97], v[220:223], v[232:235], v[82:97]
	s_add_u32 m0, s81, 0x0
	ds_read_b128 v[240:243], v211 offset:0
	global_load_lds_dwordx4 v207, s[70:71]
	v_mfma_f32_32x32x16_bf16 v[66:81], v[216:219], v[232:235], v[66:81]
	s_add_u32 m0, s81, 0x1000
	ds_read_b128 v[252:255], v215 offset:0
	global_load_lds_dwordx4 v206, s[70:71]
	v_mfma_f32_32x32x16_bf16 v[50:65], v[220:223], v[228:231], v[50:65]
	s_add_u32 m0, s81, 0x2000
	ds_read_b128 v[236:239], v211 offset:4096
	global_load_lds_dwordx4 v205, s[70:71]
	v_mfma_f32_32x32x16_bf16 v[34:49], v[216:219], v[228:231], v[34:49]
	s_add_u32 m0, s81, 0x3000
	ds_read_b128 v[248:251], v215 offset:4096
	global_load_lds_dwordx4 v204, s[70:71]
	v_mfma_f32_32x32x16_bf16 v[18:33], v[220:223], v[224:227], v[18:33]
	s_add_u32 m0, s81, 0x4000
	ds_read_b128 v[244:247], v215 offset:8192
	global_load_lds_dwordx4 v203, s[70:71]
	v_mfma_f32_32x32x16_bf16 v[2:17], v[216:219], v[224:227], v[2:17]
	s_add_u32 s78, s78, 2
	s_cmp_lt_u32 s78, 14
	s_cbranch_scc1 .Lgm_ph13_loop
	s_waitcnt lgkmcnt(1)
	v_mfma_f32_32x32x16_bf16 v[82:97], v[240:243], v[252:255], v[82:97]
	ds_read_b128 v[220:223], v210 offset:0
	s_add_u32 m0, s81, 0x5000
	s_nop 0
	global_load_lds_dwordx4 v202, s[70:71]
	v_mfma_f32_32x32x16_bf16 v[66:81], v[236:239], v[252:255], v[66:81]
	ds_read_b128 v[232:235], v214 offset:0
	s_add_u32 m0, s82, 0x0
	s_nop 0
	global_load_lds_dwordx4 v207, s[72:73]
	v_mfma_f32_32x32x16_bf16 v[50:65], v[240:243], v[248:251], v[50:65]
	ds_read_b128 v[216:219], v210 offset:4096
	s_add_u32 m0, s82, 0x1000
	s_nop 0
	global_load_lds_dwordx4 v206, s[72:73]
	v_mfma_f32_32x32x16_bf16 v[34:49], v[236:239], v[248:251], v[34:49]
	ds_read_b128 v[228:231], v214 offset:4096
	s_add_u32 m0, s82, 0x2000
	s_nop 0
	global_load_lds_dwordx4 v205, s[72:73]
	s_waitcnt lgkmcnt(4)
	v_mfma_f32_32x32x16_bf16 v[18:33], v[240:243], v[244:247], v[18:33]
	ds_read_b128 v[224:227], v214 offset:8192
	v_mfma_f32_32x32x16_bf16 v[2:17], v[236:239], v[244:247], v[2:17]
	s_add_u32 m0, s82, 0x3000
	s_nop 0
	global_load_lds_dwordx4 v204, s[72:73]
	s_waitcnt lgkmcnt(1)
	v_mfma_f32_32x32x16_bf16 v[82:97], v[220:223], v[232:235], v[82:97]
	ds_read_b128 v[240:243], v209 offset:0
	v_mfma_f32_32x32x16_bf16 v[66:81], v[216:219], v[232:235], v[66:81]
	ds_read_b128 v[252:255], v213 offset:0
	v_mfma_f32_32x32x16_bf16 v[50:65], v[220:223], v[228:231], v[50:65]
	ds_read_b128 v[236:239], v209 offset:4096
	v_mfma_f32_32x32x16_bf16 v[34:49], v[216:219], v[228:231], v[34:49]
	ds_read_b128 v[248:251], v213 offset:4096
	s_waitcnt lgkmcnt(4)
	v_mfma_f32_32x32x16_bf16 v[18:33], v[220:223], v[224:227], v[18:33]
	ds_read_b128 v[244:247], v213 offset:8192
	v_mfma_f32_32x32x16_bf16 v[2:17], v[216:219], v[224:227], v[2:17]
	s_waitcnt lgkmcnt(1)
	v_mfma_f32_32x32x16_bf16 v[82:97], v[240:243], v[252:255], v[82:97]
	ds_read_b128 v[220:223], v208 offset:0
	v_mfma_f32_32x32x16_bf16 v[66:81], v[236:239], v[252:255], v[66:81]
	ds_read_b128 v[232:235], v212 offset:0
	v_mfma_f32_32x32x16_bf16 v[50:65], v[240:243], v[248:251], v[50:65]
	ds_read_b128 v[216:219], v208 offset:4096
	v_mfma_f32_32x32x16_bf16 v[34:49], v[236:239], v[248:251], v[34:49]
	ds_read_b128 v[228:231], v212 offset:4096
	s_waitcnt lgkmcnt(4)
	v_mfma_f32_32x32x16_bf16 v[18:33], v[240:243], v[244:247], v[18:33]
	ds_read_b128 v[224:227], v212 offset:8192
	v_mfma_f32_32x32x16_bf16 v[2:17], v[236:239], v[244:247], v[2:17]
	s_waitcnt vmcnt(0) lgkmcnt(0)
	s_barrier
	v_mfma_f32_32x32x16_bf16 v[82:97], v[220:223], v[232:235], v[82:97]
	ds_read_b128 v[240:243], v211 offset:16384
	v_mfma_f32_32x32x16_bf16 v[66:81], v[216:219], v[232:235], v[66:81]
	ds_read_b128 v[252:255], v215 offset:24576
	v_mfma_f32_32x32x16_bf16 v[50:65], v[220:223], v[228:231], v[50:65]
	ds_read_b128 v[236:239], v211 offset:20480
	v_mfma_f32_32x32x16_bf16 v[34:49], v[216:219], v[228:231], v[34:49]
	ds_read_b128 v[248:251], v215 offset:28672
	v_mfma_f32_32x32x16_bf16 v[18:33], v[220:223], v[224:227], v[18:33]
	ds_read_b128 v[244:247], v215 offset:32768
	v_mfma_f32_32x32x16_bf16 v[2:17], v[216:219], v[224:227], v[2:17]
	s_waitcnt lgkmcnt(1)
	v_mfma_f32_32x32x16_bf16 v[82:97], v[240:243], v[252:255], v[82:97]
	ds_read_b128 v[220:223], v210 offset:16384
	v_mfma_f32_32x32x16_bf16 v[66:81], v[236:239], v[252:255], v[66:81]
	ds_read_b128 v[232:235], v214 offset:24576
	v_mfma_f32_32x32x16_bf16 v[50:65], v[240:243], v[248:251], v[50:65]
	ds_read_b128 v[216:219], v210 offset:20480
	v_mfma_f32_32x32x16_bf16 v[34:49], v[236:239], v[248:251], v[34:49]
	ds_read_b128 v[228:231], v214 offset:28672
	s_waitcnt lgkmcnt(4)
	v_mfma_f32_32x32x16_bf16 v[18:33], v[240:243], v[244:247], v[18:33]
	ds_read_b128 v[224:227], v214 offset:32768
	v_mfma_f32_32x32x16_bf16 v[2:17], v[236:239], v[244:247], v[2:17]
	s_waitcnt lgkmcnt(1)
	v_mfma_f32_32x32x16_bf16 v[82:97], v[220:223], v[232:235], v[82:97]
	ds_read_b128 v[240:243], v209 offset:16384
	v_mfma_f32_32x32x16_bf16 v[66:81], v[216:219], v[232:235], v[66:81]
	ds_read_b128 v[252:255], v213 offset:24576
	v_mfma_f32_32x32x16_bf16 v[50:65], v[220:223], v[228:231], v[50:65]
	ds_read_b128 v[236:239], v209 offset:20480
	v_mfma_f32_32x32x16_bf16 v[34:49], v[216:219], v[228:231], v[34:49]
	ds_read_b128 v[248:251], v213 offset:28672
	s_waitcnt lgkmcnt(4)
	v_mfma_f32_32x32x16_bf16 v[18:33], v[220:223], v[224:227], v[18:33]
	ds_read_b128 v[244:247], v213 offset:32768
	v_mfma_f32_32x32x16_bf16 v[2:17], v[216:219], v[224:227], v[2:17]
	s_waitcnt lgkmcnt(1)
	v_mfma_f32_32x32x16_bf16 v[82:97], v[240:243], v[252:255], v[82:97]
	ds_read_b128 v[220:223], v208 offset:16384
	v_mfma_f32_32x32x16_bf16 v[66:81], v[236:239], v[252:255], v[66:81]
	ds_read_b128 v[232:235], v212 offset:24576
	v_mfma_f32_32x32x16_bf16 v[50:65], v[240:243], v[248:251], v[50:65]
	ds_read_b128 v[216:219], v208 offset:20480
	v_mfma_f32_32x32x16_bf16 v[34:49], v[236:239], v[248:251], v[34:49]
	ds_read_b128 v[228:231], v212 offset:28672
	s_waitcnt lgkmcnt(4)
	v_mfma_f32_32x32x16_bf16 v[18:33], v[240:243], v[244:247], v[18:33]
	ds_read_b128 v[224:227], v212 offset:32768
	v_mfma_f32_32x32x16_bf16 v[2:17], v[236:239], v[244:247], v[2:17]
	s_waitcnt vmcnt(0) lgkmcnt(0)
	s_barrier
	v_mfma_f32_32x32x16_bf16 v[82:97], v[220:223], v[232:235], v[82:97]
	v_mfma_f32_32x32x16_bf16 v[66:81], v[216:219], v[232:235], v[66:81]
	v_mfma_f32_32x32x16_bf16 v[50:65], v[220:223], v[228:231], v[50:65]
	v_mfma_f32_32x32x16_bf16 v[34:49], v[216:219], v[228:231], v[34:49]
	v_mfma_f32_32x32x16_bf16 v[18:33], v[220:223], v[224:227], v[18:33]
	v_mfma_f32_32x32x16_bf16 v[2:17], v[216:219], v[224:227], v[2:17]
	s_nop 7
	s_nop 7
	s_setprio 0
	s_lshr_b32 s84, s64, 6
	s_cmp_lt_u32 s84, 8
	s_cbranch_scc1 G1E_ph13_U
	s_cmp_lt_u32 s84, 24
	s_cbranch_scc1 G1E_ph13_ORIG
	s_load_dwordx2 s[82:83], s[0:1], 0x98
	v_mul_f32_e32 v198, 0xbfb8aa3b, v2
	v_mul_f32_e32 v199, 0xbfb8aa3b, v3
	v_mul_f32_e32 v200, 0xbfb8aa3b, v4
	v_mul_f32_e32 v201, 0xbfb8aa3b, v5
	v_exp_f32_e32 v198, v198
	v_exp_f32_e32 v199, v199
	v_exp_f32_e32 v200, v200
	v_exp_f32_e32 v201, v201
	s_nop 0
	v_add_f32_e32 v198, 1.0, v198
	v_add_f32_e32 v199, 1.0, v199
	v_add_f32_e32 v200, 1.0, v200
	v_add_f32_e32 v201, 1.0, v201
	v_div_scale_f32 v202, s[84:85], v198, v198, v2
	v_div_scale_f32 v203, s[84:85], v199, v199, v3
	v_div_scale_f32 v204, s[84:85], v200, v200, v4
	v_div_scale_f32 v205, s[84:85], v201, v201, v5
	v_rcp_f32_e32 v206, v202
	v_rcp_f32_e32 v207, v203
	v_rcp_f32_e32 v208, v204
	v_rcp_f32_e32 v209, v205
	s_nop 0
	v_div_scale_f32 v210, vcc, v2, v198, v2
	v_fma_f32 v212, -v202, v206, 1.0
	v_fmac_f32_e32 v206, v212, v206
	v_mul_f32_e32 v211, v210, v206
	v_fma_f32 v212, -v202, v211, v210
	v_fmac_f32_e32 v211, v212, v206
	v_fma_f32 v212, -v202, v211, v210
	v_div_fmas_f32 v212, v212, v206, v211
	v_div_fixup_f32 v2, v212, v198, v2
	v_div_scale_f32 v210, vcc, v3, v199, v3
	v_fma_f32 v212, -v203, v207, 1.0
	v_fmac_f32_e32 v207, v212, v207
	v_mul_f32_e32 v211, v210, v207
	v_fma_f32 v212, -v203, v211, v210
	v_fmac_f32_e32 v211, v212, v207
	v_fma_f32 v212, -v203, v211, v210
	v_div_fmas_f32 v212, v212, v207, v211
	v_div_fixup_f32 v3, v212, v199, v3
	v_div_scale_f32 v210, vcc, v4, v200, v4
	v_fma_f32 v212, -v204, v208, 1.0
	v_fmac_f32_e32 v208, v212, v208
	v_mul_f32_e32 v211, v210, v208
	v_fma_f32 v212, -v204, v211, v210
	v_fmac_f32_e32 v211, v212, v208
	v_fma_f32 v212, -v204, v211, v210
	v_div_fmas_f32 v212, v212, v208, v211
	v_div_fixup_f32 v4, v212, v200, v4
	v_div_scale_f32 v210, vcc, v5, v201, v5
	v_fma_f32 v212, -v205, v209, 1.0
	v_fmac_f32_e32 v209, v212, v209
	v_mul_f32_e32 v211, v210, v209
	v_fma_f32 v212, -v205, v211, v210
	v_fmac_f32_e32 v211, v212, v209
	v_fma_f32 v212, -v205, v211, v210
	v_div_fmas_f32 v212, v212, v209, v211
	v_div_fixup_f32 v5, v212, v201, v5
	v_mul_f32_e32 v198, 0xbfb8aa3b, v6
	v_mul_f32_e32 v199, 0xbfb8aa3b, v7
	v_mul_f32_e32 v200, 0xbfb8aa3b, v8
	v_mul_f32_e32 v201, 0xbfb8aa3b, v9
	v_exp_f32_e32 v198, v198
	v_exp_f32_e32 v199, v199
	v_exp_f32_e32 v200, v200
	v_exp_f32_e32 v201, v201
	s_nop 0
	v_add_f32_e32 v198, 1.0, v198
	v_add_f32_e32 v199, 1.0, v199
	v_add_f32_e32 v200, 1.0, v200
	v_add_f32_e32 v201, 1.0, v201
	v_div_scale_f32 v202, s[84:85], v198, v198, v6
	v_div_scale_f32 v203, s[84:85], v199, v199, v7
	v_div_scale_f32 v204, s[84:85], v200, v200, v8
	v_div_scale_f32 v205, s[84:85], v201, v201, v9
	v_rcp_f32_e32 v206, v202
	v_rcp_f32_e32 v207, v203
	v_rcp_f32_e32 v208, v204
	v_rcp_f32_e32 v209, v205
	s_nop 0
	v_div_scale_f32 v210, vcc, v6, v198, v6
	v_fma_f32 v212, -v202, v206, 1.0
	v_fmac_f32_e32 v206, v212, v206
	v_mul_f32_e32 v211, v210, v206
	v_fma_f32 v212, -v202, v211, v210
	v_fmac_f32_e32 v211, v212, v206
	v_fma_f32 v212, -v202, v211, v210
	v_div_fmas_f32 v212, v212, v206, v211
	v_div_fixup_f32 v6, v212, v198, v6
	v_div_scale_f32 v210, vcc, v7, v199, v7
	v_fma_f32 v212, -v203, v207, 1.0
	v_fmac_f32_e32 v207, v212, v207
	v_mul_f32_e32 v211, v210, v207
	v_fma_f32 v212, -v203, v211, v210
	v_fmac_f32_e32 v211, v212, v207
	v_fma_f32 v212, -v203, v211, v210
	v_div_fmas_f32 v212, v212, v207, v211
	v_div_fixup_f32 v7, v212, v199, v7
	v_div_scale_f32 v210, vcc, v8, v200, v8
	v_fma_f32 v212, -v204, v208, 1.0
	v_fmac_f32_e32 v208, v212, v208
	v_mul_f32_e32 v211, v210, v208
	v_fma_f32 v212, -v204, v211, v210
	v_fmac_f32_e32 v211, v212, v208
	v_fma_f32 v212, -v204, v211, v210
	v_div_fmas_f32 v212, v212, v208, v211
	v_div_fixup_f32 v8, v212, v200, v8
	v_div_scale_f32 v210, vcc, v9, v201, v9
	v_fma_f32 v212, -v205, v209, 1.0
	v_fmac_f32_e32 v209, v212, v209
	v_mul_f32_e32 v211, v210, v209
	v_fma_f32 v212, -v205, v211, v210
	v_fmac_f32_e32 v211, v212, v209
	v_fma_f32 v212, -v205, v211, v210
	v_div_fmas_f32 v212, v212, v209, v211
	v_div_fixup_f32 v9, v212, v201, v9
	v_mul_f32_e32 v198, 0xbfb8aa3b, v10
	v_mul_f32_e32 v199, 0xbfb8aa3b, v11
	v_mul_f32_e32 v200, 0xbfb8aa3b, v12
	v_mul_f32_e32 v201, 0xbfb8aa3b, v13
	v_exp_f32_e32 v198, v198
	v_exp_f32_e32 v199, v199
	v_exp_f32_e32 v200, v200
	v_exp_f32_e32 v201, v201
	s_nop 0
	v_add_f32_e32 v198, 1.0, v198
	v_add_f32_e32 v199, 1.0, v199
	v_add_f32_e32 v200, 1.0, v200
	v_add_f32_e32 v201, 1.0, v201
	v_div_scale_f32 v202, s[84:85], v198, v198, v10
	v_div_scale_f32 v203, s[84:85], v199, v199, v11
	v_div_scale_f32 v204, s[84:85], v200, v200, v12
	v_div_scale_f32 v205, s[84:85], v201, v201, v13
	v_rcp_f32_e32 v206, v202
	v_rcp_f32_e32 v207, v203
	v_rcp_f32_e32 v208, v204
	v_rcp_f32_e32 v209, v205
	s_nop 0
	v_div_scale_f32 v210, vcc, v10, v198, v10
	v_fma_f32 v212, -v202, v206, 1.0
	v_fmac_f32_e32 v206, v212, v206
	v_mul_f32_e32 v211, v210, v206
	v_fma_f32 v212, -v202, v211, v210
	v_fmac_f32_e32 v211, v212, v206
	v_fma_f32 v212, -v202, v211, v210
	v_div_fmas_f32 v212, v212, v206, v211
	v_div_fixup_f32 v10, v212, v198, v10
	v_div_scale_f32 v210, vcc, v11, v199, v11
	v_fma_f32 v212, -v203, v207, 1.0
	v_fmac_f32_e32 v207, v212, v207
	v_mul_f32_e32 v211, v210, v207
	v_fma_f32 v212, -v203, v211, v210
	v_fmac_f32_e32 v211, v212, v207
	v_fma_f32 v212, -v203, v211, v210
	v_div_fmas_f32 v212, v212, v207, v211
	v_div_fixup_f32 v11, v212, v199, v11
	v_div_scale_f32 v210, vcc, v12, v200, v12
	v_fma_f32 v212, -v204, v208, 1.0
	v_fmac_f32_e32 v208, v212, v208
	v_mul_f32_e32 v211, v210, v208
	v_fma_f32 v212, -v204, v211, v210
	v_fmac_f32_e32 v211, v212, v208
	v_fma_f32 v212, -v204, v211, v210
	v_div_fmas_f32 v212, v212, v208, v211
	v_div_fixup_f32 v12, v212, v200, v12
	v_div_scale_f32 v210, vcc, v13, v201, v13
	v_fma_f32 v212, -v205, v209, 1.0
	v_fmac_f32_e32 v209, v212, v209
	v_mul_f32_e32 v211, v210, v209
	v_fma_f32 v212, -v205, v211, v210
	v_fmac_f32_e32 v211, v212, v209
	v_fma_f32 v212, -v205, v211, v210
	v_div_fmas_f32 v212, v212, v209, v211
	v_div_fixup_f32 v13, v212, v201, v13
	v_mul_f32_e32 v198, 0xbfb8aa3b, v14
	v_mul_f32_e32 v199, 0xbfb8aa3b, v15
	v_mul_f32_e32 v200, 0xbfb8aa3b, v16
	v_mul_f32_e32 v201, 0xbfb8aa3b, v17
	v_exp_f32_e32 v198, v198
	v_exp_f32_e32 v199, v199
	v_exp_f32_e32 v200, v200
	v_exp_f32_e32 v201, v201
	s_nop 0
	v_add_f32_e32 v198, 1.0, v198
	v_add_f32_e32 v199, 1.0, v199
	v_add_f32_e32 v200, 1.0, v200
	v_add_f32_e32 v201, 1.0, v201
	v_div_scale_f32 v202, s[84:85], v198, v198, v14
	v_div_scale_f32 v203, s[84:85], v199, v199, v15
	v_div_scale_f32 v204, s[84:85], v200, v200, v16
	v_div_scale_f32 v205, s[84:85], v201, v201, v17
	v_rcp_f32_e32 v206, v202
	v_rcp_f32_e32 v207, v203
	v_rcp_f32_e32 v208, v204
	v_rcp_f32_e32 v209, v205
	s_nop 0
	v_div_scale_f32 v210, vcc, v14, v198, v14
	v_fma_f32 v212, -v202, v206, 1.0
	v_fmac_f32_e32 v206, v212, v206
	v_mul_f32_e32 v211, v210, v206
	v_fma_f32 v212, -v202, v211, v210
	v_fmac_f32_e32 v211, v212, v206
	v_fma_f32 v212, -v202, v211, v210
	v_div_fmas_f32 v212, v212, v206, v211
	v_div_fixup_f32 v14, v212, v198, v14
	v_div_scale_f32 v210, vcc, v15, v199, v15
	v_fma_f32 v212, -v203, v207, 1.0
	v_fmac_f32_e32 v207, v212, v207
	v_mul_f32_e32 v211, v210, v207
	v_fma_f32 v212, -v203, v211, v210
	v_fmac_f32_e32 v211, v212, v207
	v_fma_f32 v212, -v203, v211, v210
	v_div_fmas_f32 v212, v212, v207, v211
	v_div_fixup_f32 v15, v212, v199, v15
	v_div_scale_f32 v210, vcc, v16, v200, v16
	v_fma_f32 v212, -v204, v208, 1.0
	v_fmac_f32_e32 v208, v212, v208
	v_mul_f32_e32 v211, v210, v208
	v_fma_f32 v212, -v204, v211, v210
	v_fmac_f32_e32 v211, v212, v208
	v_fma_f32 v212, -v204, v211, v210
	v_div_fmas_f32 v212, v212, v208, v211
	v_div_fixup_f32 v16, v212, v200, v16
	v_div_scale_f32 v210, vcc, v17, v201, v17
	v_fma_f32 v212, -v205, v209, 1.0
	v_fmac_f32_e32 v209, v212, v209
	v_mul_f32_e32 v211, v210, v209
	v_fma_f32 v212, -v205, v211, v210
	v_fmac_f32_e32 v211, v212, v209
	v_fma_f32 v212, -v205, v211, v210
	v_div_fmas_f32 v212, v212, v209, v211
	v_div_fixup_f32 v17, v212, v201, v17
	v_mul_f32_e32 v198, 0xbfb8aa3b, v18
	v_mul_f32_e32 v199, 0xbfb8aa3b, v19
	v_mul_f32_e32 v200, 0xbfb8aa3b, v20
	v_mul_f32_e32 v201, 0xbfb8aa3b, v21
	v_exp_f32_e32 v198, v198
	v_exp_f32_e32 v199, v199
	v_exp_f32_e32 v200, v200
	v_exp_f32_e32 v201, v201
	s_nop 0
	v_add_f32_e32 v198, 1.0, v198
	v_add_f32_e32 v199, 1.0, v199
	v_add_f32_e32 v200, 1.0, v200
	v_add_f32_e32 v201, 1.0, v201
	v_div_scale_f32 v202, s[84:85], v198, v198, v18
	v_div_scale_f32 v203, s[84:85], v199, v199, v19
	v_div_scale_f32 v204, s[84:85], v200, v200, v20
	v_div_scale_f32 v205, s[84:85], v201, v201, v21
	v_rcp_f32_e32 v206, v202
	v_rcp_f32_e32 v207, v203
	v_rcp_f32_e32 v208, v204
	v_rcp_f32_e32 v209, v205
	s_nop 0
	v_div_scale_f32 v210, vcc, v18, v198, v18
	v_fma_f32 v212, -v202, v206, 1.0
	v_fmac_f32_e32 v206, v212, v206
	v_mul_f32_e32 v211, v210, v206
	v_fma_f32 v212, -v202, v211, v210
	v_fmac_f32_e32 v211, v212, v206
	v_fma_f32 v212, -v202, v211, v210
	v_div_fmas_f32 v212, v212, v206, v211
	v_div_fixup_f32 v18, v212, v198, v18
	v_div_scale_f32 v210, vcc, v19, v199, v19
	v_fma_f32 v212, -v203, v207, 1.0
	v_fmac_f32_e32 v207, v212, v207
	v_mul_f32_e32 v211, v210, v207
	v_fma_f32 v212, -v203, v211, v210
	v_fmac_f32_e32 v211, v212, v207
	v_fma_f32 v212, -v203, v211, v210
	v_div_fmas_f32 v212, v212, v207, v211
	v_div_fixup_f32 v19, v212, v199, v19
	v_div_scale_f32 v210, vcc, v20, v200, v20
	v_fma_f32 v212, -v204, v208, 1.0
	v_fmac_f32_e32 v208, v212, v208
	v_mul_f32_e32 v211, v210, v208
	v_fma_f32 v212, -v204, v211, v210
	v_fmac_f32_e32 v211, v212, v208
	v_fma_f32 v212, -v204, v211, v210
	v_div_fmas_f32 v212, v212, v208, v211
	v_div_fixup_f32 v20, v212, v200, v20
	v_div_scale_f32 v210, vcc, v21, v201, v21
	v_fma_f32 v212, -v205, v209, 1.0
	v_fmac_f32_e32 v209, v212, v209
	v_mul_f32_e32 v211, v210, v209
	v_fma_f32 v212, -v205, v211, v210
	v_fmac_f32_e32 v211, v212, v209
	v_fma_f32 v212, -v205, v211, v210
	v_div_fmas_f32 v212, v212, v209, v211
	v_div_fixup_f32 v21, v212, v201, v21
	v_mul_f32_e32 v198, 0xbfb8aa3b, v22
	v_mul_f32_e32 v199, 0xbfb8aa3b, v23
	v_mul_f32_e32 v200, 0xbfb8aa3b, v24
	v_mul_f32_e32 v201, 0xbfb8aa3b, v25
	v_exp_f32_e32 v198, v198
	v_exp_f32_e32 v199, v199
	v_exp_f32_e32 v200, v200
	v_exp_f32_e32 v201, v201
	s_nop 0
	v_add_f32_e32 v198, 1.0, v198
	v_add_f32_e32 v199, 1.0, v199
	v_add_f32_e32 v200, 1.0, v200
	v_add_f32_e32 v201, 1.0, v201
	v_div_scale_f32 v202, s[84:85], v198, v198, v22
	v_div_scale_f32 v203, s[84:85], v199, v199, v23
	v_div_scale_f32 v204, s[84:85], v200, v200, v24
	v_div_scale_f32 v205, s[84:85], v201, v201, v25
	v_rcp_f32_e32 v206, v202
	v_rcp_f32_e32 v207, v203
	v_rcp_f32_e32 v208, v204
	v_rcp_f32_e32 v209, v205
	s_nop 0
	v_div_scale_f32 v210, vcc, v22, v198, v22
	v_fma_f32 v212, -v202, v206, 1.0
	v_fmac_f32_e32 v206, v212, v206
	v_mul_f32_e32 v211, v210, v206
	v_fma_f32 v212, -v202, v211, v210
	v_fmac_f32_e32 v211, v212, v206
	v_fma_f32 v212, -v202, v211, v210
	v_div_fmas_f32 v212, v212, v206, v211
	v_div_fixup_f32 v22, v212, v198, v22
	v_div_scale_f32 v210, vcc, v23, v199, v23
	v_fma_f32 v212, -v203, v207, 1.0
	v_fmac_f32_e32 v207, v212, v207
	v_mul_f32_e32 v211, v210, v207
	v_fma_f32 v212, -v203, v211, v210
	v_fmac_f32_e32 v211, v212, v207
	v_fma_f32 v212, -v203, v211, v210
	v_div_fmas_f32 v212, v212, v207, v211
	v_div_fixup_f32 v23, v212, v199, v23
	v_div_scale_f32 v210, vcc, v24, v200, v24
	v_fma_f32 v212, -v204, v208, 1.0
	v_fmac_f32_e32 v208, v212, v208
	v_mul_f32_e32 v211, v210, v208
	v_fma_f32 v212, -v204, v211, v210
	v_fmac_f32_e32 v211, v212, v208
	v_fma_f32 v212, -v204, v211, v210
	v_div_fmas_f32 v212, v212, v208, v211
	v_div_fixup_f32 v24, v212, v200, v24
	v_div_scale_f32 v210, vcc, v25, v201, v25
	v_fma_f32 v212, -v205, v209, 1.0
	v_fmac_f32_e32 v209, v212, v209
	v_mul_f32_e32 v211, v210, v209
	v_fma_f32 v212, -v205, v211, v210
	v_fmac_f32_e32 v211, v212, v209
	v_fma_f32 v212, -v205, v211, v210
	v_div_fmas_f32 v212, v212, v209, v211
	v_div_fixup_f32 v25, v212, v201, v25
	v_mul_f32_e32 v198, 0xbfb8aa3b, v26
	v_mul_f32_e32 v199, 0xbfb8aa3b, v27
	v_mul_f32_e32 v200, 0xbfb8aa3b, v28
	v_mul_f32_e32 v201, 0xbfb8aa3b, v29
	v_exp_f32_e32 v198, v198
	v_exp_f32_e32 v199, v199
	v_exp_f32_e32 v200, v200
	v_exp_f32_e32 v201, v201
	s_nop 0
	v_add_f32_e32 v198, 1.0, v198
	v_add_f32_e32 v199, 1.0, v199
	v_add_f32_e32 v200, 1.0, v200
	v_add_f32_e32 v201, 1.0, v201
	v_div_scale_f32 v202, s[84:85], v198, v198, v26
	v_div_scale_f32 v203, s[84:85], v199, v199, v27
	v_div_scale_f32 v204, s[84:85], v200, v200, v28
	v_div_scale_f32 v205, s[84:85], v201, v201, v29
	v_rcp_f32_e32 v206, v202
	v_rcp_f32_e32 v207, v203
	v_rcp_f32_e32 v208, v204
	v_rcp_f32_e32 v209, v205
	s_nop 0
	v_div_scale_f32 v210, vcc, v26, v198, v26
	v_fma_f32 v212, -v202, v206, 1.0
	v_fmac_f32_e32 v206, v212, v206
	v_mul_f32_e32 v211, v210, v206
	v_fma_f32 v212, -v202, v211, v210
	v_fmac_f32_e32 v211, v212, v206
	v_fma_f32 v212, -v202, v211, v210
	v_div_fmas_f32 v212, v212, v206, v211
	v_div_fixup_f32 v26, v212, v198, v26
	v_div_scale_f32 v210, vcc, v27, v199, v27
	v_fma_f32 v212, -v203, v207, 1.0
	v_fmac_f32_e32 v207, v212, v207
	v_mul_f32_e32 v211, v210, v207
	v_fma_f32 v212, -v203, v211, v210
	v_fmac_f32_e32 v211, v212, v207
	v_fma_f32 v212, -v203, v211, v210
	v_div_fmas_f32 v212, v212, v207, v211
	v_div_fixup_f32 v27, v212, v199, v27
	v_div_scale_f32 v210, vcc, v28, v200, v28
	v_fma_f32 v212, -v204, v208, 1.0
	v_fmac_f32_e32 v208, v212, v208
	v_mul_f32_e32 v211, v210, v208
	v_fma_f32 v212, -v204, v211, v210
	v_fmac_f32_e32 v211, v212, v208
	v_fma_f32 v212, -v204, v211, v210
	v_div_fmas_f32 v212, v212, v208, v211
	v_div_fixup_f32 v28, v212, v200, v28
	v_div_scale_f32 v210, vcc, v29, v201, v29
	v_fma_f32 v212, -v205, v209, 1.0
	v_fmac_f32_e32 v209, v212, v209
	v_mul_f32_e32 v211, v210, v209
	v_fma_f32 v212, -v205, v211, v210
	v_fmac_f32_e32 v211, v212, v209
	v_fma_f32 v212, -v205, v211, v210
	v_div_fmas_f32 v212, v212, v209, v211
	v_div_fixup_f32 v29, v212, v201, v29
	v_mul_f32_e32 v198, 0xbfb8aa3b, v30
	v_mul_f32_e32 v199, 0xbfb8aa3b, v31
	v_mul_f32_e32 v200, 0xbfb8aa3b, v32
	v_mul_f32_e32 v201, 0xbfb8aa3b, v33
	v_exp_f32_e32 v198, v198
	v_exp_f32_e32 v199, v199
	v_exp_f32_e32 v200, v200
	v_exp_f32_e32 v201, v201
	s_nop 0
	v_add_f32_e32 v198, 1.0, v198
	v_add_f32_e32 v199, 1.0, v199
	v_add_f32_e32 v200, 1.0, v200
	v_add_f32_e32 v201, 1.0, v201
	v_div_scale_f32 v202, s[84:85], v198, v198, v30
	v_div_scale_f32 v203, s[84:85], v199, v199, v31
	v_div_scale_f32 v204, s[84:85], v200, v200, v32
	v_div_scale_f32 v205, s[84:85], v201, v201, v33
	v_rcp_f32_e32 v206, v202
	v_rcp_f32_e32 v207, v203
	v_rcp_f32_e32 v208, v204
	v_rcp_f32_e32 v209, v205
	s_nop 0
	v_div_scale_f32 v210, vcc, v30, v198, v30
	v_fma_f32 v212, -v202, v206, 1.0
	v_fmac_f32_e32 v206, v212, v206
	v_mul_f32_e32 v211, v210, v206
	v_fma_f32 v212, -v202, v211, v210
	v_fmac_f32_e32 v211, v212, v206
	v_fma_f32 v212, -v202, v211, v210
	v_div_fmas_f32 v212, v212, v206, v211
	v_div_fixup_f32 v30, v212, v198, v30
	v_div_scale_f32 v210, vcc, v31, v199, v31
	v_fma_f32 v212, -v203, v207, 1.0
	v_fmac_f32_e32 v207, v212, v207
	v_mul_f32_e32 v211, v210, v207
	v_fma_f32 v212, -v203, v211, v210
	v_fmac_f32_e32 v211, v212, v207
	v_fma_f32 v212, -v203, v211, v210
	v_div_fmas_f32 v212, v212, v207, v211
	v_div_fixup_f32 v31, v212, v199, v31
	v_div_scale_f32 v210, vcc, v32, v200, v32
	v_fma_f32 v212, -v204, v208, 1.0
	v_fmac_f32_e32 v208, v212, v208
	v_mul_f32_e32 v211, v210, v208
	v_fma_f32 v212, -v204, v211, v210
	v_fmac_f32_e32 v211, v212, v208
	v_fma_f32 v212, -v204, v211, v210
	v_div_fmas_f32 v212, v212, v208, v211
	v_div_fixup_f32 v32, v212, v200, v32
	v_div_scale_f32 v210, vcc, v33, v201, v33
	v_fma_f32 v212, -v205, v209, 1.0
	v_fmac_f32_e32 v209, v212, v209
	v_mul_f32_e32 v211, v210, v209
	v_fma_f32 v212, -v205, v211, v210
	v_fmac_f32_e32 v211, v212, v209
	v_fma_f32 v212, -v205, v211, v210
	v_div_fmas_f32 v212, v212, v209, v211
	v_div_fixup_f32 v33, v212, v201, v33
	v_mul_f32_e32 v198, 0xbfb8aa3b, v34
	v_mul_f32_e32 v199, 0xbfb8aa3b, v35
	v_mul_f32_e32 v200, 0xbfb8aa3b, v36
	v_mul_f32_e32 v201, 0xbfb8aa3b, v37
	v_exp_f32_e32 v198, v198
	v_exp_f32_e32 v199, v199
	v_exp_f32_e32 v200, v200
	v_exp_f32_e32 v201, v201
	s_nop 0
	v_add_f32_e32 v198, 1.0, v198
	v_add_f32_e32 v199, 1.0, v199
	v_add_f32_e32 v200, 1.0, v200
	v_add_f32_e32 v201, 1.0, v201
	v_div_scale_f32 v202, s[84:85], v198, v198, v34
	v_div_scale_f32 v203, s[84:85], v199, v199, v35
	v_div_scale_f32 v204, s[84:85], v200, v200, v36
	v_div_scale_f32 v205, s[84:85], v201, v201, v37
	v_rcp_f32_e32 v206, v202
	v_rcp_f32_e32 v207, v203
	v_rcp_f32_e32 v208, v204
	v_rcp_f32_e32 v209, v205
	s_nop 0
	v_div_scale_f32 v210, vcc, v34, v198, v34
	v_fma_f32 v212, -v202, v206, 1.0
	v_fmac_f32_e32 v206, v212, v206
	v_mul_f32_e32 v211, v210, v206
	v_fma_f32 v212, -v202, v211, v210
	v_fmac_f32_e32 v211, v212, v206
	v_fma_f32 v212, -v202, v211, v210
	v_div_fmas_f32 v212, v212, v206, v211
	v_div_fixup_f32 v34, v212, v198, v34
	v_div_scale_f32 v210, vcc, v35, v199, v35
	v_fma_f32 v212, -v203, v207, 1.0
	v_fmac_f32_e32 v207, v212, v207
	v_mul_f32_e32 v211, v210, v207
	v_fma_f32 v212, -v203, v211, v210
	v_fmac_f32_e32 v211, v212, v207
	v_fma_f32 v212, -v203, v211, v210
	v_div_fmas_f32 v212, v212, v207, v211
	v_div_fixup_f32 v35, v212, v199, v35
	v_div_scale_f32 v210, vcc, v36, v200, v36
	v_fma_f32 v212, -v204, v208, 1.0
	v_fmac_f32_e32 v208, v212, v208
	v_mul_f32_e32 v211, v210, v208
	v_fma_f32 v212, -v204, v211, v210
	v_fmac_f32_e32 v211, v212, v208
	v_fma_f32 v212, -v204, v211, v210
	v_div_fmas_f32 v212, v212, v208, v211
	v_div_fixup_f32 v36, v212, v200, v36
	v_div_scale_f32 v210, vcc, v37, v201, v37
	v_fma_f32 v212, -v205, v209, 1.0
	v_fmac_f32_e32 v209, v212, v209
	v_mul_f32_e32 v211, v210, v209
	v_fma_f32 v212, -v205, v211, v210
	v_fmac_f32_e32 v211, v212, v209
	v_fma_f32 v212, -v205, v211, v210
	v_div_fmas_f32 v212, v212, v209, v211
	v_div_fixup_f32 v37, v212, v201, v37
	v_mul_f32_e32 v198, 0xbfb8aa3b, v38
	v_mul_f32_e32 v199, 0xbfb8aa3b, v39
	v_mul_f32_e32 v200, 0xbfb8aa3b, v40
	v_mul_f32_e32 v201, 0xbfb8aa3b, v41
	v_exp_f32_e32 v198, v198
	v_exp_f32_e32 v199, v199
	v_exp_f32_e32 v200, v200
	v_exp_f32_e32 v201, v201
	s_nop 0
	v_add_f32_e32 v198, 1.0, v198
	v_add_f32_e32 v199, 1.0, v199
	v_add_f32_e32 v200, 1.0, v200
	v_add_f32_e32 v201, 1.0, v201
	v_div_scale_f32 v202, s[84:85], v198, v198, v38
	v_div_scale_f32 v203, s[84:85], v199, v199, v39
	v_div_scale_f32 v204, s[84:85], v200, v200, v40
	v_div_scale_f32 v205, s[84:85], v201, v201, v41
	v_rcp_f32_e32 v206, v202
	v_rcp_f32_e32 v207, v203
	v_rcp_f32_e32 v208, v204
	v_rcp_f32_e32 v209, v205
	s_nop 0
	v_div_scale_f32 v210, vcc, v38, v198, v38
	v_fma_f32 v212, -v202, v206, 1.0
	v_fmac_f32_e32 v206, v212, v206
	v_mul_f32_e32 v211, v210, v206
	v_fma_f32 v212, -v202, v211, v210
	v_fmac_f32_e32 v211, v212, v206
	v_fma_f32 v212, -v202, v211, v210
	v_div_fmas_f32 v212, v212, v206, v211
	v_div_fixup_f32 v38, v212, v198, v38
	v_div_scale_f32 v210, vcc, v39, v199, v39
	v_fma_f32 v212, -v203, v207, 1.0
	v_fmac_f32_e32 v207, v212, v207
	v_mul_f32_e32 v211, v210, v207
	v_fma_f32 v212, -v203, v211, v210
	v_fmac_f32_e32 v211, v212, v207
	v_fma_f32 v212, -v203, v211, v210
	v_div_fmas_f32 v212, v212, v207, v211
	v_div_fixup_f32 v39, v212, v199, v39
	v_div_scale_f32 v210, vcc, v40, v200, v40
	v_fma_f32 v212, -v204, v208, 1.0
	v_fmac_f32_e32 v208, v212, v208
	v_mul_f32_e32 v211, v210, v208
	v_fma_f32 v212, -v204, v211, v210
	v_fmac_f32_e32 v211, v212, v208
	v_fma_f32 v212, -v204, v211, v210
	v_div_fmas_f32 v212, v212, v208, v211
	v_div_fixup_f32 v40, v212, v200, v40
	v_div_scale_f32 v210, vcc, v41, v201, v41
	v_fma_f32 v212, -v205, v209, 1.0
	v_fmac_f32_e32 v209, v212, v209
	v_mul_f32_e32 v211, v210, v209
	v_fma_f32 v212, -v205, v211, v210
	v_fmac_f32_e32 v211, v212, v209
	v_fma_f32 v212, -v205, v211, v210
	v_div_fmas_f32 v212, v212, v209, v211
	v_div_fixup_f32 v41, v212, v201, v41
	v_mul_f32_e32 v198, 0xbfb8aa3b, v42
	v_mul_f32_e32 v199, 0xbfb8aa3b, v43
	v_mul_f32_e32 v200, 0xbfb8aa3b, v44
	v_mul_f32_e32 v201, 0xbfb8aa3b, v45
	v_exp_f32_e32 v198, v198
	v_exp_f32_e32 v199, v199
	v_exp_f32_e32 v200, v200
	v_exp_f32_e32 v201, v201
	s_nop 0
	v_add_f32_e32 v198, 1.0, v198
	v_add_f32_e32 v199, 1.0, v199
	v_add_f32_e32 v200, 1.0, v200
	v_add_f32_e32 v201, 1.0, v201
	v_div_scale_f32 v202, s[84:85], v198, v198, v42
	v_div_scale_f32 v203, s[84:85], v199, v199, v43
	v_div_scale_f32 v204, s[84:85], v200, v200, v44
	v_div_scale_f32 v205, s[84:85], v201, v201, v45
	v_rcp_f32_e32 v206, v202
	v_rcp_f32_e32 v207, v203
	v_rcp_f32_e32 v208, v204
	v_rcp_f32_e32 v209, v205
	s_nop 0
	v_div_scale_f32 v210, vcc, v42, v198, v42
	v_fma_f32 v212, -v202, v206, 1.0
	v_fmac_f32_e32 v206, v212, v206
	v_mul_f32_e32 v211, v210, v206
	v_fma_f32 v212, -v202, v211, v210
	v_fmac_f32_e32 v211, v212, v206
	v_fma_f32 v212, -v202, v211, v210
	v_div_fmas_f32 v212, v212, v206, v211
	v_div_fixup_f32 v42, v212, v198, v42
	v_div_scale_f32 v210, vcc, v43, v199, v43
	v_fma_f32 v212, -v203, v207, 1.0
	v_fmac_f32_e32 v207, v212, v207
	v_mul_f32_e32 v211, v210, v207
	v_fma_f32 v212, -v203, v211, v210
	v_fmac_f32_e32 v211, v212, v207
	v_fma_f32 v212, -v203, v211, v210
	v_div_fmas_f32 v212, v212, v207, v211
	v_div_fixup_f32 v43, v212, v199, v43
	v_div_scale_f32 v210, vcc, v44, v200, v44
	v_fma_f32 v212, -v204, v208, 1.0
	v_fmac_f32_e32 v208, v212, v208
	v_mul_f32_e32 v211, v210, v208
	v_fma_f32 v212, -v204, v211, v210
	v_fmac_f32_e32 v211, v212, v208
	v_fma_f32 v212, -v204, v211, v210
	v_div_fmas_f32 v212, v212, v208, v211
	v_div_fixup_f32 v44, v212, v200, v44
	v_div_scale_f32 v210, vcc, v45, v201, v45
	v_fma_f32 v212, -v205, v209, 1.0
	v_fmac_f32_e32 v209, v212, v209
	v_mul_f32_e32 v211, v210, v209
	v_fma_f32 v212, -v205, v211, v210
	v_fmac_f32_e32 v211, v212, v209
	v_fma_f32 v212, -v205, v211, v210
	v_div_fmas_f32 v212, v212, v209, v211
	v_div_fixup_f32 v45, v212, v201, v45
	v_mul_f32_e32 v198, 0xbfb8aa3b, v46
	v_mul_f32_e32 v199, 0xbfb8aa3b, v47
	v_mul_f32_e32 v200, 0xbfb8aa3b, v48
	v_mul_f32_e32 v201, 0xbfb8aa3b, v49
	v_exp_f32_e32 v198, v198
	v_exp_f32_e32 v199, v199
	v_exp_f32_e32 v200, v200
	v_exp_f32_e32 v201, v201
	s_nop 0
	v_add_f32_e32 v198, 1.0, v198
	v_add_f32_e32 v199, 1.0, v199
	v_add_f32_e32 v200, 1.0, v200
	v_add_f32_e32 v201, 1.0, v201
	v_div_scale_f32 v202, s[84:85], v198, v198, v46
	v_div_scale_f32 v203, s[84:85], v199, v199, v47
	v_div_scale_f32 v204, s[84:85], v200, v200, v48
	v_div_scale_f32 v205, s[84:85], v201, v201, v49
	v_rcp_f32_e32 v206, v202
	v_rcp_f32_e32 v207, v203
	v_rcp_f32_e32 v208, v204
	v_rcp_f32_e32 v209, v205
	s_nop 0
	v_div_scale_f32 v210, vcc, v46, v198, v46
	v_fma_f32 v212, -v202, v206, 1.0
	v_fmac_f32_e32 v206, v212, v206
	v_mul_f32_e32 v211, v210, v206
	v_fma_f32 v212, -v202, v211, v210
	v_fmac_f32_e32 v211, v212, v206
	v_fma_f32 v212, -v202, v211, v210
	v_div_fmas_f32 v212, v212, v206, v211
	v_div_fixup_f32 v46, v212, v198, v46
	v_div_scale_f32 v210, vcc, v47, v199, v47
	v_fma_f32 v212, -v203, v207, 1.0
	v_fmac_f32_e32 v207, v212, v207
	v_mul_f32_e32 v211, v210, v207
	v_fma_f32 v212, -v203, v211, v210
	v_fmac_f32_e32 v211, v212, v207
	v_fma_f32 v212, -v203, v211, v210
	v_div_fmas_f32 v212, v212, v207, v211
	v_div_fixup_f32 v47, v212, v199, v47
	v_div_scale_f32 v210, vcc, v48, v200, v48
	v_fma_f32 v212, -v204, v208, 1.0
	v_fmac_f32_e32 v208, v212, v208
	v_mul_f32_e32 v211, v210, v208
	v_fma_f32 v212, -v204, v211, v210
	v_fmac_f32_e32 v211, v212, v208
	v_fma_f32 v212, -v204, v211, v210
	v_div_fmas_f32 v212, v212, v208, v211
	v_div_fixup_f32 v48, v212, v200, v48
	v_div_scale_f32 v210, vcc, v49, v201, v49
	v_fma_f32 v212, -v205, v209, 1.0
	v_fmac_f32_e32 v209, v212, v209
	v_mul_f32_e32 v211, v210, v209
	v_fma_f32 v212, -v205, v211, v210
	v_fmac_f32_e32 v211, v212, v209
	v_fma_f32 v212, -v205, v211, v210
	v_div_fmas_f32 v212, v212, v209, v211
	v_div_fixup_f32 v49, v212, v201, v49
	v_mul_f32_e32 v198, 0xbfb8aa3b, v50
	v_mul_f32_e32 v199, 0xbfb8aa3b, v51
	v_mul_f32_e32 v200, 0xbfb8aa3b, v52
	v_mul_f32_e32 v201, 0xbfb8aa3b, v53
	v_exp_f32_e32 v198, v198
	v_exp_f32_e32 v199, v199
	v_exp_f32_e32 v200, v200
	v_exp_f32_e32 v201, v201
	s_nop 0
	v_add_f32_e32 v198, 1.0, v198
	v_add_f32_e32 v199, 1.0, v199
	v_add_f32_e32 v200, 1.0, v200
	v_add_f32_e32 v201, 1.0, v201
	v_div_scale_f32 v202, s[84:85], v198, v198, v50
	v_div_scale_f32 v203, s[84:85], v199, v199, v51
	v_div_scale_f32 v204, s[84:85], v200, v200, v52
	v_div_scale_f32 v205, s[84:85], v201, v201, v53
	v_rcp_f32_e32 v206, v202
	v_rcp_f32_e32 v207, v203
	v_rcp_f32_e32 v208, v204
	v_rcp_f32_e32 v209, v205
	s_nop 0
	v_div_scale_f32 v210, vcc, v50, v198, v50
	v_fma_f32 v212, -v202, v206, 1.0
	v_fmac_f32_e32 v206, v212, v206
	v_mul_f32_e32 v211, v210, v206
	v_fma_f32 v212, -v202, v211, v210
	v_fmac_f32_e32 v211, v212, v206
	v_fma_f32 v212, -v202, v211, v210
	v_div_fmas_f32 v212, v212, v206, v211
	v_div_fixup_f32 v50, v212, v198, v50
	v_div_scale_f32 v210, vcc, v51, v199, v51
	v_fma_f32 v212, -v203, v207, 1.0
	v_fmac_f32_e32 v207, v212, v207
	v_mul_f32_e32 v211, v210, v207
	v_fma_f32 v212, -v203, v211, v210
	v_fmac_f32_e32 v211, v212, v207
	v_fma_f32 v212, -v203, v211, v210
	v_div_fmas_f32 v212, v212, v207, v211
	v_div_fixup_f32 v51, v212, v199, v51
	v_div_scale_f32 v210, vcc, v52, v200, v52
	v_fma_f32 v212, -v204, v208, 1.0
	v_fmac_f32_e32 v208, v212, v208
	v_mul_f32_e32 v211, v210, v208
	v_fma_f32 v212, -v204, v211, v210
	v_fmac_f32_e32 v211, v212, v208
	v_fma_f32 v212, -v204, v211, v210
	v_div_fmas_f32 v212, v212, v208, v211
	v_div_fixup_f32 v52, v212, v200, v52
	v_div_scale_f32 v210, vcc, v53, v201, v53
	v_fma_f32 v212, -v205, v209, 1.0
	v_fmac_f32_e32 v209, v212, v209
	v_mul_f32_e32 v211, v210, v209
	v_fma_f32 v212, -v205, v211, v210
	v_fmac_f32_e32 v211, v212, v209
	v_fma_f32 v212, -v205, v211, v210
	v_div_fmas_f32 v212, v212, v209, v211
	v_div_fixup_f32 v53, v212, v201, v53
	v_mul_f32_e32 v198, 0xbfb8aa3b, v54
	v_mul_f32_e32 v199, 0xbfb8aa3b, v55
	v_mul_f32_e32 v200, 0xbfb8aa3b, v56
	v_mul_f32_e32 v201, 0xbfb8aa3b, v57
	v_exp_f32_e32 v198, v198
	v_exp_f32_e32 v199, v199
	v_exp_f32_e32 v200, v200
	v_exp_f32_e32 v201, v201
	s_nop 0
	v_add_f32_e32 v198, 1.0, v198
	v_add_f32_e32 v199, 1.0, v199
	v_add_f32_e32 v200, 1.0, v200
	v_add_f32_e32 v201, 1.0, v201
	v_div_scale_f32 v202, s[84:85], v198, v198, v54
	v_div_scale_f32 v203, s[84:85], v199, v199, v55
	v_div_scale_f32 v204, s[84:85], v200, v200, v56
	v_div_scale_f32 v205, s[84:85], v201, v201, v57
	v_rcp_f32_e32 v206, v202
	v_rcp_f32_e32 v207, v203
	v_rcp_f32_e32 v208, v204
	v_rcp_f32_e32 v209, v205
	s_nop 0
	v_div_scale_f32 v210, vcc, v54, v198, v54
	v_fma_f32 v212, -v202, v206, 1.0
	v_fmac_f32_e32 v206, v212, v206
	v_mul_f32_e32 v211, v210, v206
	v_fma_f32 v212, -v202, v211, v210
	v_fmac_f32_e32 v211, v212, v206
	v_fma_f32 v212, -v202, v211, v210
	v_div_fmas_f32 v212, v212, v206, v211
	v_div_fixup_f32 v54, v212, v198, v54
	v_div_scale_f32 v210, vcc, v55, v199, v55
	v_fma_f32 v212, -v203, v207, 1.0
	v_fmac_f32_e32 v207, v212, v207
	v_mul_f32_e32 v211, v210, v207
	v_fma_f32 v212, -v203, v211, v210
	v_fmac_f32_e32 v211, v212, v207
	v_fma_f32 v212, -v203, v211, v210
	v_div_fmas_f32 v212, v212, v207, v211
	v_div_fixup_f32 v55, v212, v199, v55
	v_div_scale_f32 v210, vcc, v56, v200, v56
	v_fma_f32 v212, -v204, v208, 1.0
	v_fmac_f32_e32 v208, v212, v208
	v_mul_f32_e32 v211, v210, v208
	v_fma_f32 v212, -v204, v211, v210
	v_fmac_f32_e32 v211, v212, v208
	v_fma_f32 v212, -v204, v211, v210
	v_div_fmas_f32 v212, v212, v208, v211
	v_div_fixup_f32 v56, v212, v200, v56
	v_div_scale_f32 v210, vcc, v57, v201, v57
	v_fma_f32 v212, -v205, v209, 1.0
	v_fmac_f32_e32 v209, v212, v209
	v_mul_f32_e32 v211, v210, v209
	v_fma_f32 v212, -v205, v211, v210
	v_fmac_f32_e32 v211, v212, v209
	v_fma_f32 v212, -v205, v211, v210
	v_div_fmas_f32 v212, v212, v209, v211
	v_div_fixup_f32 v57, v212, v201, v57
	v_mul_f32_e32 v198, 0xbfb8aa3b, v58
	v_mul_f32_e32 v199, 0xbfb8aa3b, v59
	v_mul_f32_e32 v200, 0xbfb8aa3b, v60
	v_mul_f32_e32 v201, 0xbfb8aa3b, v61
	v_exp_f32_e32 v198, v198
	v_exp_f32_e32 v199, v199
	v_exp_f32_e32 v200, v200
	v_exp_f32_e32 v201, v201
	s_nop 0
	v_add_f32_e32 v198, 1.0, v198
	v_add_f32_e32 v199, 1.0, v199
	v_add_f32_e32 v200, 1.0, v200
	v_add_f32_e32 v201, 1.0, v201
	v_div_scale_f32 v202, s[84:85], v198, v198, v58
	v_div_scale_f32 v203, s[84:85], v199, v199, v59
	v_div_scale_f32 v204, s[84:85], v200, v200, v60
	v_div_scale_f32 v205, s[84:85], v201, v201, v61
	v_rcp_f32_e32 v206, v202
	v_rcp_f32_e32 v207, v203
	v_rcp_f32_e32 v208, v204
	v_rcp_f32_e32 v209, v205
	s_nop 0
	v_div_scale_f32 v210, vcc, v58, v198, v58
	v_fma_f32 v212, -v202, v206, 1.0
	v_fmac_f32_e32 v206, v212, v206
	v_mul_f32_e32 v211, v210, v206
	v_fma_f32 v212, -v202, v211, v210
	v_fmac_f32_e32 v211, v212, v206
	v_fma_f32 v212, -v202, v211, v210
	v_div_fmas_f32 v212, v212, v206, v211
	v_div_fixup_f32 v58, v212, v198, v58
	v_div_scale_f32 v210, vcc, v59, v199, v59
	v_fma_f32 v212, -v203, v207, 1.0
	v_fmac_f32_e32 v207, v212, v207
	v_mul_f32_e32 v211, v210, v207
	v_fma_f32 v212, -v203, v211, v210
	v_fmac_f32_e32 v211, v212, v207
	v_fma_f32 v212, -v203, v211, v210
	v_div_fmas_f32 v212, v212, v207, v211
	v_div_fixup_f32 v59, v212, v199, v59
	v_div_scale_f32 v210, vcc, v60, v200, v60
	v_fma_f32 v212, -v204, v208, 1.0
	v_fmac_f32_e32 v208, v212, v208
	v_mul_f32_e32 v211, v210, v208
	v_fma_f32 v212, -v204, v211, v210
	v_fmac_f32_e32 v211, v212, v208
	v_fma_f32 v212, -v204, v211, v210
	v_div_fmas_f32 v212, v212, v208, v211
	v_div_fixup_f32 v60, v212, v200, v60
	v_div_scale_f32 v210, vcc, v61, v201, v61
	v_fma_f32 v212, -v205, v209, 1.0
	v_fmac_f32_e32 v209, v212, v209
	v_mul_f32_e32 v211, v210, v209
	v_fma_f32 v212, -v205, v211, v210
	v_fmac_f32_e32 v211, v212, v209
	v_fma_f32 v212, -v205, v211, v210
	v_div_fmas_f32 v212, v212, v209, v211
	v_div_fixup_f32 v61, v212, v201, v61
	v_mul_f32_e32 v198, 0xbfb8aa3b, v62
	v_mul_f32_e32 v199, 0xbfb8aa3b, v63
	v_mul_f32_e32 v200, 0xbfb8aa3b, v64
	v_mul_f32_e32 v201, 0xbfb8aa3b, v65
	v_exp_f32_e32 v198, v198
	v_exp_f32_e32 v199, v199
	v_exp_f32_e32 v200, v200
	v_exp_f32_e32 v201, v201
	s_nop 0
	v_add_f32_e32 v198, 1.0, v198
	v_add_f32_e32 v199, 1.0, v199
	v_add_f32_e32 v200, 1.0, v200
	v_add_f32_e32 v201, 1.0, v201
	v_div_scale_f32 v202, s[84:85], v198, v198, v62
	v_div_scale_f32 v203, s[84:85], v199, v199, v63
	v_div_scale_f32 v204, s[84:85], v200, v200, v64
	v_div_scale_f32 v205, s[84:85], v201, v201, v65
	v_rcp_f32_e32 v206, v202
	v_rcp_f32_e32 v207, v203
	v_rcp_f32_e32 v208, v204
	v_rcp_f32_e32 v209, v205
	s_nop 0
	v_div_scale_f32 v210, vcc, v62, v198, v62
	v_fma_f32 v212, -v202, v206, 1.0
	v_fmac_f32_e32 v206, v212, v206
	v_mul_f32_e32 v211, v210, v206
	v_fma_f32 v212, -v202, v211, v210
	v_fmac_f32_e32 v211, v212, v206
	v_fma_f32 v212, -v202, v211, v210
	v_div_fmas_f32 v212, v212, v206, v211
	v_div_fixup_f32 v62, v212, v198, v62
	v_div_scale_f32 v210, vcc, v63, v199, v63
	v_fma_f32 v212, -v203, v207, 1.0
	v_fmac_f32_e32 v207, v212, v207
	v_mul_f32_e32 v211, v210, v207
	v_fma_f32 v212, -v203, v211, v210
	v_fmac_f32_e32 v211, v212, v207
	v_fma_f32 v212, -v203, v211, v210
	v_div_fmas_f32 v212, v212, v207, v211
	v_div_fixup_f32 v63, v212, v199, v63
	v_div_scale_f32 v210, vcc, v64, v200, v64
	v_fma_f32 v212, -v204, v208, 1.0
	v_fmac_f32_e32 v208, v212, v208
	v_mul_f32_e32 v211, v210, v208
	v_fma_f32 v212, -v204, v211, v210
	v_fmac_f32_e32 v211, v212, v208
	v_fma_f32 v212, -v204, v211, v210
	v_div_fmas_f32 v212, v212, v208, v211
	v_div_fixup_f32 v64, v212, v200, v64
	v_div_scale_f32 v210, vcc, v65, v201, v65
	v_fma_f32 v212, -v205, v209, 1.0
	v_fmac_f32_e32 v209, v212, v209
	v_mul_f32_e32 v211, v210, v209
	v_fma_f32 v212, -v205, v211, v210
	v_fmac_f32_e32 v211, v212, v209
	v_fma_f32 v212, -v205, v211, v210
	v_div_fmas_f32 v212, v212, v209, v211
	v_div_fixup_f32 v65, v212, v201, v65
	v_mul_f32_e32 v198, 0xbfb8aa3b, v66
	v_mul_f32_e32 v199, 0xbfb8aa3b, v67
	v_mul_f32_e32 v200, 0xbfb8aa3b, v68
	v_mul_f32_e32 v201, 0xbfb8aa3b, v69
	v_exp_f32_e32 v198, v198
	v_exp_f32_e32 v199, v199
	v_exp_f32_e32 v200, v200
	v_exp_f32_e32 v201, v201
	s_nop 0
	v_add_f32_e32 v198, 1.0, v198
	v_add_f32_e32 v199, 1.0, v199
	v_add_f32_e32 v200, 1.0, v200
	v_add_f32_e32 v201, 1.0, v201
	v_div_scale_f32 v202, s[84:85], v198, v198, v66
	v_div_scale_f32 v203, s[84:85], v199, v199, v67
	v_div_scale_f32 v204, s[84:85], v200, v200, v68
	v_div_scale_f32 v205, s[84:85], v201, v201, v69
	v_rcp_f32_e32 v206, v202
	v_rcp_f32_e32 v207, v203
	v_rcp_f32_e32 v208, v204
	v_rcp_f32_e32 v209, v205
	s_nop 0
	v_div_scale_f32 v210, vcc, v66, v198, v66
	v_fma_f32 v212, -v202, v206, 1.0
	v_fmac_f32_e32 v206, v212, v206
	v_mul_f32_e32 v211, v210, v206
	v_fma_f32 v212, -v202, v211, v210
	v_fmac_f32_e32 v211, v212, v206
	v_fma_f32 v212, -v202, v211, v210
	v_div_fmas_f32 v212, v212, v206, v211
	v_div_fixup_f32 v66, v212, v198, v66
	v_div_scale_f32 v210, vcc, v67, v199, v67
	v_fma_f32 v212, -v203, v207, 1.0
	v_fmac_f32_e32 v207, v212, v207
	v_mul_f32_e32 v211, v210, v207
	v_fma_f32 v212, -v203, v211, v210
	v_fmac_f32_e32 v211, v212, v207
	v_fma_f32 v212, -v203, v211, v210
	v_div_fmas_f32 v212, v212, v207, v211
	v_div_fixup_f32 v67, v212, v199, v67
	v_div_scale_f32 v210, vcc, v68, v200, v68
	v_fma_f32 v212, -v204, v208, 1.0
	v_fmac_f32_e32 v208, v212, v208
	v_mul_f32_e32 v211, v210, v208
	v_fma_f32 v212, -v204, v211, v210
	v_fmac_f32_e32 v211, v212, v208
	v_fma_f32 v212, -v204, v211, v210
	v_div_fmas_f32 v212, v212, v208, v211
	v_div_fixup_f32 v68, v212, v200, v68
	v_div_scale_f32 v210, vcc, v69, v201, v69
	v_fma_f32 v212, -v205, v209, 1.0
	v_fmac_f32_e32 v209, v212, v209
	v_mul_f32_e32 v211, v210, v209
	v_fma_f32 v212, -v205, v211, v210
	v_fmac_f32_e32 v211, v212, v209
	v_fma_f32 v212, -v205, v211, v210
	v_div_fmas_f32 v212, v212, v209, v211
	v_div_fixup_f32 v69, v212, v201, v69
	v_mul_f32_e32 v198, 0xbfb8aa3b, v70
	v_mul_f32_e32 v199, 0xbfb8aa3b, v71
	v_mul_f32_e32 v200, 0xbfb8aa3b, v72
	v_mul_f32_e32 v201, 0xbfb8aa3b, v73
	v_exp_f32_e32 v198, v198
	v_exp_f32_e32 v199, v199
	v_exp_f32_e32 v200, v200
	v_exp_f32_e32 v201, v201
	s_nop 0
	v_add_f32_e32 v198, 1.0, v198
	v_add_f32_e32 v199, 1.0, v199
	v_add_f32_e32 v200, 1.0, v200
	v_add_f32_e32 v201, 1.0, v201
	v_div_scale_f32 v202, s[84:85], v198, v198, v70
	v_div_scale_f32 v203, s[84:85], v199, v199, v71
	v_div_scale_f32 v204, s[84:85], v200, v200, v72
	v_div_scale_f32 v205, s[84:85], v201, v201, v73
	v_rcp_f32_e32 v206, v202
	v_rcp_f32_e32 v207, v203
	v_rcp_f32_e32 v208, v204
	v_rcp_f32_e32 v209, v205
	s_nop 0
	v_div_scale_f32 v210, vcc, v70, v198, v70
	v_fma_f32 v212, -v202, v206, 1.0
	v_fmac_f32_e32 v206, v212, v206
	v_mul_f32_e32 v211, v210, v206
	v_fma_f32 v212, -v202, v211, v210
	v_fmac_f32_e32 v211, v212, v206
	v_fma_f32 v212, -v202, v211, v210
	v_div_fmas_f32 v212, v212, v206, v211
	v_div_fixup_f32 v70, v212, v198, v70
	v_div_scale_f32 v210, vcc, v71, v199, v71
	v_fma_f32 v212, -v203, v207, 1.0
	v_fmac_f32_e32 v207, v212, v207
	v_mul_f32_e32 v211, v210, v207
	v_fma_f32 v212, -v203, v211, v210
	v_fmac_f32_e32 v211, v212, v207
	v_fma_f32 v212, -v203, v211, v210
	v_div_fmas_f32 v212, v212, v207, v211
	v_div_fixup_f32 v71, v212, v199, v71
	v_div_scale_f32 v210, vcc, v72, v200, v72
	v_fma_f32 v212, -v204, v208, 1.0
	v_fmac_f32_e32 v208, v212, v208
	v_mul_f32_e32 v211, v210, v208
	v_fma_f32 v212, -v204, v211, v210
	v_fmac_f32_e32 v211, v212, v208
	v_fma_f32 v212, -v204, v211, v210
	v_div_fmas_f32 v212, v212, v208, v211
	v_div_fixup_f32 v72, v212, v200, v72
	v_div_scale_f32 v210, vcc, v73, v201, v73
	v_fma_f32 v212, -v205, v209, 1.0
	v_fmac_f32_e32 v209, v212, v209
	v_mul_f32_e32 v211, v210, v209
	v_fma_f32 v212, -v205, v211, v210
	v_fmac_f32_e32 v211, v212, v209
	v_fma_f32 v212, -v205, v211, v210
	v_div_fmas_f32 v212, v212, v209, v211
	v_div_fixup_f32 v73, v212, v201, v73
	v_mul_f32_e32 v198, 0xbfb8aa3b, v74
	v_mul_f32_e32 v199, 0xbfb8aa3b, v75
	v_mul_f32_e32 v200, 0xbfb8aa3b, v76
	v_mul_f32_e32 v201, 0xbfb8aa3b, v77
	v_exp_f32_e32 v198, v198
	v_exp_f32_e32 v199, v199
	v_exp_f32_e32 v200, v200
	v_exp_f32_e32 v201, v201
	s_nop 0
	v_add_f32_e32 v198, 1.0, v198
	v_add_f32_e32 v199, 1.0, v199
	v_add_f32_e32 v200, 1.0, v200
	v_add_f32_e32 v201, 1.0, v201
	v_div_scale_f32 v202, s[84:85], v198, v198, v74
	v_div_scale_f32 v203, s[84:85], v199, v199, v75
	v_div_scale_f32 v204, s[84:85], v200, v200, v76
	v_div_scale_f32 v205, s[84:85], v201, v201, v77
	v_rcp_f32_e32 v206, v202
	v_rcp_f32_e32 v207, v203
	v_rcp_f32_e32 v208, v204
	v_rcp_f32_e32 v209, v205
	s_nop 0
	v_div_scale_f32 v210, vcc, v74, v198, v74
	v_fma_f32 v212, -v202, v206, 1.0
	v_fmac_f32_e32 v206, v212, v206
	v_mul_f32_e32 v211, v210, v206
	v_fma_f32 v212, -v202, v211, v210
	v_fmac_f32_e32 v211, v212, v206
	v_fma_f32 v212, -v202, v211, v210
	v_div_fmas_f32 v212, v212, v206, v211
	v_div_fixup_f32 v74, v212, v198, v74
	v_div_scale_f32 v210, vcc, v75, v199, v75
	v_fma_f32 v212, -v203, v207, 1.0
	v_fmac_f32_e32 v207, v212, v207
	v_mul_f32_e32 v211, v210, v207
	v_fma_f32 v212, -v203, v211, v210
	v_fmac_f32_e32 v211, v212, v207
	v_fma_f32 v212, -v203, v211, v210
	v_div_fmas_f32 v212, v212, v207, v211
	v_div_fixup_f32 v75, v212, v199, v75
	v_div_scale_f32 v210, vcc, v76, v200, v76
	v_fma_f32 v212, -v204, v208, 1.0
	v_fmac_f32_e32 v208, v212, v208
	v_mul_f32_e32 v211, v210, v208
	v_fma_f32 v212, -v204, v211, v210
	v_fmac_f32_e32 v211, v212, v208
	v_fma_f32 v212, -v204, v211, v210
	v_div_fmas_f32 v212, v212, v208, v211
	v_div_fixup_f32 v76, v212, v200, v76
	v_div_scale_f32 v210, vcc, v77, v201, v77
	v_fma_f32 v212, -v205, v209, 1.0
	v_fmac_f32_e32 v209, v212, v209
	v_mul_f32_e32 v211, v210, v209
	v_fma_f32 v212, -v205, v211, v210
	v_fmac_f32_e32 v211, v212, v209
	v_fma_f32 v212, -v205, v211, v210
	v_div_fmas_f32 v212, v212, v209, v211
	v_div_fixup_f32 v77, v212, v201, v77
	v_mul_f32_e32 v198, 0xbfb8aa3b, v78
	v_mul_f32_e32 v199, 0xbfb8aa3b, v79
	v_mul_f32_e32 v200, 0xbfb8aa3b, v80
	v_mul_f32_e32 v201, 0xbfb8aa3b, v81
	v_exp_f32_e32 v198, v198
	v_exp_f32_e32 v199, v199
	v_exp_f32_e32 v200, v200
	v_exp_f32_e32 v201, v201
	s_nop 0
	v_add_f32_e32 v198, 1.0, v198
	v_add_f32_e32 v199, 1.0, v199
	v_add_f32_e32 v200, 1.0, v200
	v_add_f32_e32 v201, 1.0, v201
	v_div_scale_f32 v202, s[84:85], v198, v198, v78
	v_div_scale_f32 v203, s[84:85], v199, v199, v79
	v_div_scale_f32 v204, s[84:85], v200, v200, v80
	v_div_scale_f32 v205, s[84:85], v201, v201, v81
	v_rcp_f32_e32 v206, v202
	v_rcp_f32_e32 v207, v203
	v_rcp_f32_e32 v208, v204
	v_rcp_f32_e32 v209, v205
	s_nop 0
	v_div_scale_f32 v210, vcc, v78, v198, v78
	v_fma_f32 v212, -v202, v206, 1.0
	v_fmac_f32_e32 v206, v212, v206
	v_mul_f32_e32 v211, v210, v206
	v_fma_f32 v212, -v202, v211, v210
	v_fmac_f32_e32 v211, v212, v206
	v_fma_f32 v212, -v202, v211, v210
	v_div_fmas_f32 v212, v212, v206, v211
	v_div_fixup_f32 v78, v212, v198, v78
	v_div_scale_f32 v210, vcc, v79, v199, v79
	v_fma_f32 v212, -v203, v207, 1.0
	v_fmac_f32_e32 v207, v212, v207
	v_mul_f32_e32 v211, v210, v207
	v_fma_f32 v212, -v203, v211, v210
	v_fmac_f32_e32 v211, v212, v207
	v_fma_f32 v212, -v203, v211, v210
	v_div_fmas_f32 v212, v212, v207, v211
	v_div_fixup_f32 v79, v212, v199, v79
	v_div_scale_f32 v210, vcc, v80, v200, v80
	v_fma_f32 v212, -v204, v208, 1.0
	v_fmac_f32_e32 v208, v212, v208
	v_mul_f32_e32 v211, v210, v208
	v_fma_f32 v212, -v204, v211, v210
	v_fmac_f32_e32 v211, v212, v208
	v_fma_f32 v212, -v204, v211, v210
	v_div_fmas_f32 v212, v212, v208, v211
	v_div_fixup_f32 v80, v212, v200, v80
	v_div_scale_f32 v210, vcc, v81, v201, v81
	v_fma_f32 v212, -v205, v209, 1.0
	v_fmac_f32_e32 v209, v212, v209
	v_mul_f32_e32 v211, v210, v209
	v_fma_f32 v212, -v205, v211, v210
	v_fmac_f32_e32 v211, v212, v209
	v_fma_f32 v212, -v205, v211, v210
	v_div_fmas_f32 v212, v212, v209, v211
	v_div_fixup_f32 v81, v212, v201, v81
	v_mul_f32_e32 v198, 0xbfb8aa3b, v82
	v_mul_f32_e32 v199, 0xbfb8aa3b, v83
	v_mul_f32_e32 v200, 0xbfb8aa3b, v84
	v_mul_f32_e32 v201, 0xbfb8aa3b, v85
	v_exp_f32_e32 v198, v198
	v_exp_f32_e32 v199, v199
	v_exp_f32_e32 v200, v200
	v_exp_f32_e32 v201, v201
	s_nop 0
	v_add_f32_e32 v198, 1.0, v198
	v_add_f32_e32 v199, 1.0, v199
	v_add_f32_e32 v200, 1.0, v200
	v_add_f32_e32 v201, 1.0, v201
	v_div_scale_f32 v202, s[84:85], v198, v198, v82
	v_div_scale_f32 v203, s[84:85], v199, v199, v83
	v_div_scale_f32 v204, s[84:85], v200, v200, v84
	v_div_scale_f32 v205, s[84:85], v201, v201, v85
	v_rcp_f32_e32 v206, v202
	v_rcp_f32_e32 v207, v203
	v_rcp_f32_e32 v208, v204
	v_rcp_f32_e32 v209, v205
	s_nop 0
	v_div_scale_f32 v210, vcc, v82, v198, v82
	v_fma_f32 v212, -v202, v206, 1.0
	v_fmac_f32_e32 v206, v212, v206
	v_mul_f32_e32 v211, v210, v206
	v_fma_f32 v212, -v202, v211, v210
	v_fmac_f32_e32 v211, v212, v206
	v_fma_f32 v212, -v202, v211, v210
	v_div_fmas_f32 v212, v212, v206, v211
	v_div_fixup_f32 v82, v212, v198, v82
	v_div_scale_f32 v210, vcc, v83, v199, v83
	v_fma_f32 v212, -v203, v207, 1.0
	v_fmac_f32_e32 v207, v212, v207
	v_mul_f32_e32 v211, v210, v207
	v_fma_f32 v212, -v203, v211, v210
	v_fmac_f32_e32 v211, v212, v207
	v_fma_f32 v212, -v203, v211, v210
	v_div_fmas_f32 v212, v212, v207, v211
	v_div_fixup_f32 v83, v212, v199, v83
	v_div_scale_f32 v210, vcc, v84, v200, v84
	v_fma_f32 v212, -v204, v208, 1.0
	v_fmac_f32_e32 v208, v212, v208
	v_mul_f32_e32 v211, v210, v208
	v_fma_f32 v212, -v204, v211, v210
	v_fmac_f32_e32 v211, v212, v208
	v_fma_f32 v212, -v204, v211, v210
	v_div_fmas_f32 v212, v212, v208, v211
	v_div_fixup_f32 v84, v212, v200, v84
	v_div_scale_f32 v210, vcc, v85, v201, v85
	v_fma_f32 v212, -v205, v209, 1.0
	v_fmac_f32_e32 v209, v212, v209
	v_mul_f32_e32 v211, v210, v209
	v_fma_f32 v212, -v205, v211, v210
	v_fmac_f32_e32 v211, v212, v209
	v_fma_f32 v212, -v205, v211, v210
	v_div_fmas_f32 v212, v212, v209, v211
	v_div_fixup_f32 v85, v212, v201, v85
	v_mul_f32_e32 v198, 0xbfb8aa3b, v86
	v_mul_f32_e32 v199, 0xbfb8aa3b, v87
	v_mul_f32_e32 v200, 0xbfb8aa3b, v88
	v_mul_f32_e32 v201, 0xbfb8aa3b, v89
	v_exp_f32_e32 v198, v198
	v_exp_f32_e32 v199, v199
	v_exp_f32_e32 v200, v200
	v_exp_f32_e32 v201, v201
	s_nop 0
	v_add_f32_e32 v198, 1.0, v198
	v_add_f32_e32 v199, 1.0, v199
	v_add_f32_e32 v200, 1.0, v200
	v_add_f32_e32 v201, 1.0, v201
	v_div_scale_f32 v202, s[84:85], v198, v198, v86
	v_div_scale_f32 v203, s[84:85], v199, v199, v87
	v_div_scale_f32 v204, s[84:85], v200, v200, v88
	v_div_scale_f32 v205, s[84:85], v201, v201, v89
	v_rcp_f32_e32 v206, v202
	v_rcp_f32_e32 v207, v203
	v_rcp_f32_e32 v208, v204
	v_rcp_f32_e32 v209, v205
	s_nop 0
	v_div_scale_f32 v210, vcc, v86, v198, v86
	v_fma_f32 v212, -v202, v206, 1.0
	v_fmac_f32_e32 v206, v212, v206
	v_mul_f32_e32 v211, v210, v206
	v_fma_f32 v212, -v202, v211, v210
	v_fmac_f32_e32 v211, v212, v206
	v_fma_f32 v212, -v202, v211, v210
	v_div_fmas_f32 v212, v212, v206, v211
	v_div_fixup_f32 v86, v212, v198, v86
	v_div_scale_f32 v210, vcc, v87, v199, v87
	v_fma_f32 v212, -v203, v207, 1.0
	v_fmac_f32_e32 v207, v212, v207
	v_mul_f32_e32 v211, v210, v207
	v_fma_f32 v212, -v203, v211, v210
	v_fmac_f32_e32 v211, v212, v207
	v_fma_f32 v212, -v203, v211, v210
	v_div_fmas_f32 v212, v212, v207, v211
	v_div_fixup_f32 v87, v212, v199, v87
	v_div_scale_f32 v210, vcc, v88, v200, v88
	v_fma_f32 v212, -v204, v208, 1.0
	v_fmac_f32_e32 v208, v212, v208
	v_mul_f32_e32 v211, v210, v208
	v_fma_f32 v212, -v204, v211, v210
	v_fmac_f32_e32 v211, v212, v208
	v_fma_f32 v212, -v204, v211, v210
	v_div_fmas_f32 v212, v212, v208, v211
	v_div_fixup_f32 v88, v212, v200, v88
	v_div_scale_f32 v210, vcc, v89, v201, v89
	v_fma_f32 v212, -v205, v209, 1.0
	v_fmac_f32_e32 v209, v212, v209
	v_mul_f32_e32 v211, v210, v209
	v_fma_f32 v212, -v205, v211, v210
	v_fmac_f32_e32 v211, v212, v209
	v_fma_f32 v212, -v205, v211, v210
	v_div_fmas_f32 v212, v212, v209, v211
	v_div_fixup_f32 v89, v212, v201, v89
	v_mul_f32_e32 v198, 0xbfb8aa3b, v90
	v_mul_f32_e32 v199, 0xbfb8aa3b, v91
	v_mul_f32_e32 v200, 0xbfb8aa3b, v92
	v_mul_f32_e32 v201, 0xbfb8aa3b, v93
	v_exp_f32_e32 v198, v198
	v_exp_f32_e32 v199, v199
	v_exp_f32_e32 v200, v200
	v_exp_f32_e32 v201, v201
	s_nop 0
	v_add_f32_e32 v198, 1.0, v198
	v_add_f32_e32 v199, 1.0, v199
	v_add_f32_e32 v200, 1.0, v200
	v_add_f32_e32 v201, 1.0, v201
	v_div_scale_f32 v202, s[84:85], v198, v198, v90
	v_div_scale_f32 v203, s[84:85], v199, v199, v91
	v_div_scale_f32 v204, s[84:85], v200, v200, v92
	v_div_scale_f32 v205, s[84:85], v201, v201, v93
	v_rcp_f32_e32 v206, v202
	v_rcp_f32_e32 v207, v203
	v_rcp_f32_e32 v208, v204
	v_rcp_f32_e32 v209, v205
	s_nop 0
	v_div_scale_f32 v210, vcc, v90, v198, v90
	v_fma_f32 v212, -v202, v206, 1.0
	v_fmac_f32_e32 v206, v212, v206
	v_mul_f32_e32 v211, v210, v206
	v_fma_f32 v212, -v202, v211, v210
	v_fmac_f32_e32 v211, v212, v206
	v_fma_f32 v212, -v202, v211, v210
	v_div_fmas_f32 v212, v212, v206, v211
	v_div_fixup_f32 v90, v212, v198, v90
	v_div_scale_f32 v210, vcc, v91, v199, v91
	v_fma_f32 v212, -v203, v207, 1.0
	v_fmac_f32_e32 v207, v212, v207
	v_mul_f32_e32 v211, v210, v207
	v_fma_f32 v212, -v203, v211, v210
	v_fmac_f32_e32 v211, v212, v207
	v_fma_f32 v212, -v203, v211, v210
	v_div_fmas_f32 v212, v212, v207, v211
	v_div_fixup_f32 v91, v212, v199, v91
	v_div_scale_f32 v210, vcc, v92, v200, v92
	v_fma_f32 v212, -v204, v208, 1.0
	v_fmac_f32_e32 v208, v212, v208
	v_mul_f32_e32 v211, v210, v208
	v_fma_f32 v212, -v204, v211, v210
	v_fmac_f32_e32 v211, v212, v208
	v_fma_f32 v212, -v204, v211, v210
	v_div_fmas_f32 v212, v212, v208, v211
	v_div_fixup_f32 v92, v212, v200, v92
	v_div_scale_f32 v210, vcc, v93, v201, v93
	v_fma_f32 v212, -v205, v209, 1.0
	v_fmac_f32_e32 v209, v212, v209
	v_mul_f32_e32 v211, v210, v209
	v_fma_f32 v212, -v205, v211, v210
	v_fmac_f32_e32 v211, v212, v209
	v_fma_f32 v212, -v205, v211, v210
	v_div_fmas_f32 v212, v212, v209, v211
	v_div_fixup_f32 v93, v212, v201, v93
	v_mul_f32_e32 v198, 0xbfb8aa3b, v94
	v_mul_f32_e32 v199, 0xbfb8aa3b, v95
	v_mul_f32_e32 v200, 0xbfb8aa3b, v96
	v_mul_f32_e32 v201, 0xbfb8aa3b, v97
	v_exp_f32_e32 v198, v198
	v_exp_f32_e32 v199, v199
	v_exp_f32_e32 v200, v200
	v_exp_f32_e32 v201, v201
	s_nop 0
	v_add_f32_e32 v198, 1.0, v198
	v_add_f32_e32 v199, 1.0, v199
	v_add_f32_e32 v200, 1.0, v200
	v_add_f32_e32 v201, 1.0, v201
	v_div_scale_f32 v202, s[84:85], v198, v198, v94
	v_div_scale_f32 v203, s[84:85], v199, v199, v95
	v_div_scale_f32 v204, s[84:85], v200, v200, v96
	v_div_scale_f32 v205, s[84:85], v201, v201, v97
	v_rcp_f32_e32 v206, v202
	v_rcp_f32_e32 v207, v203
	v_rcp_f32_e32 v208, v204
	v_rcp_f32_e32 v209, v205
	s_nop 0
	v_div_scale_f32 v210, vcc, v94, v198, v94
	v_fma_f32 v212, -v202, v206, 1.0
	v_fmac_f32_e32 v206, v212, v206
	v_mul_f32_e32 v211, v210, v206
	v_fma_f32 v212, -v202, v211, v210
	v_fmac_f32_e32 v211, v212, v206
	v_fma_f32 v212, -v202, v211, v210
	v_div_fmas_f32 v212, v212, v206, v211
	v_div_fixup_f32 v94, v212, v198, v94
	v_div_scale_f32 v210, vcc, v95, v199, v95
	v_fma_f32 v212, -v203, v207, 1.0
	v_fmac_f32_e32 v207, v212, v207
	v_mul_f32_e32 v211, v210, v207
	v_fma_f32 v212, -v203, v211, v210
	v_fmac_f32_e32 v211, v212, v207
	v_fma_f32 v212, -v203, v211, v210
	v_div_fmas_f32 v212, v212, v207, v211
	v_div_fixup_f32 v95, v212, v199, v95
	v_div_scale_f32 v210, vcc, v96, v200, v96
	v_fma_f32 v212, -v204, v208, 1.0
	v_fmac_f32_e32 v208, v212, v208
	v_mul_f32_e32 v211, v210, v208
	v_fma_f32 v212, -v204, v211, v210
	v_fmac_f32_e32 v211, v212, v208
	v_fma_f32 v212, -v204, v211, v210
	v_div_fmas_f32 v212, v212, v208, v211
	v_div_fixup_f32 v96, v212, v200, v96
	v_div_scale_f32 v210, vcc, v97, v201, v97
	v_fma_f32 v212, -v205, v209, 1.0
	v_fmac_f32_e32 v209, v212, v209
	v_mul_f32_e32 v211, v210, v209
	v_fma_f32 v212, -v205, v211, v210
	v_fmac_f32_e32 v211, v212, v209
	v_fma_f32 v212, -v205, v211, v210
	v_div_fmas_f32 v212, v212, v209, v211
	v_div_fixup_f32 v97, v212, v201, v97
	v_and_b32_e32 v223, 31, v0
	v_mul_u32_u24_e32 v220, 0x110, v223
	v_bfe_u32 v223, v0, 5, 1
	v_lshl_add_u32 v220, v223, 4, v220
	v_bfe_u32 v224, v0, 6, 2
	v_mul_u32_u24_e32 v223, 0x2200, v224
	v_add_u32_e32 v220, v220, v223
	v_bfe_u32 v222, v0, 4, 2
	v_mul_u32_u24_e32 v221, 0x110, v222
	v_add_u32_e32 v221, v221, v223
	v_and_b32_e32 v223, 15, v0
	v_lshl_add_u32 v221, v223, 4, v221
	s_lshr_b32 s85, s64, 6
	s_sub_u32 s85, s85, 24
	s_lshl_b32 s85, s85, 8
	s_and_b32 s84, s64, 63
	s_mulk_i32 s84, 0xc0
	v_lshrrev_b32_e32 v224, 1, v224
	v_mul_u32_u24_e32 v224, 0x60, v224
	v_add3_u32 v222, v222, v224, s84
	v_lshlrev_b32_e32 v222, 11, v222
	v_lshl_add_u32 v222, v223, 3, v222
	v_bfe_u32 v223, v0, 6, 1
	v_lshl_add_u32 v222, v223, 7, v222
	v_add_u32_e32 v222, s85, v222
	ds_write_b128 v220, v[82:85]
	ds_write_b128 v220, v[86:89] offset:32
	ds_write_b128 v220, v[90:93] offset:64
	ds_write_b128 v220, v[94:97] offset:96
	ds_write_b128 v220, v[66:69] offset:128
	ds_write_b128 v220, v[70:73] offset:160
	ds_write_b128 v220, v[74:77] offset:192
	ds_write_b128 v220, v[78:81] offset:224
	v_mov_b32_e32 v230, v222
	v_add_u32_e32 v231, 0x2000, v222
	v_add_u32_e32 v232, 0x4000, v222
	v_add_u32_e32 v233, 0x6000, v222
	v_add_u32_e32 v234, 0x8000, v222
	v_add_u32_e32 v235, 0xa000, v222
	v_add_u32_e32 v236, 0xc000, v222
	v_add_u32_e32 v237, 0xe000, v222
	s_waitcnt lgkmcnt(0)
	ds_read_b128 v[82:85], v221
	ds_read_b128 v[86:89], v221 offset:1088
	ds_read_b128 v[90:93], v221 offset:2176
	ds_read_b128 v[94:97], v221 offset:3264
	ds_read_b128 v[66:69], v221 offset:4352
	ds_read_b128 v[70:73], v221 offset:5440
	ds_read_b128 v[74:77], v221 offset:6528
	ds_read_b128 v[78:81], v221 offset:7616
	s_waitcnt lgkmcnt(7)
	v_cvt_pk_bf16_f32 v82, v82, v83
	v_cvt_pk_bf16_f32 v83, v84, v85
	global_store_dwordx2 v230, v[82:83], s[82:83]
	s_waitcnt lgkmcnt(6)
	v_cvt_pk_bf16_f32 v86, v86, v87
	v_cvt_pk_bf16_f32 v87, v88, v89
	global_store_dwordx2 v231, v[86:87], s[82:83]
	s_waitcnt lgkmcnt(5)
	v_cvt_pk_bf16_f32 v90, v90, v91
	v_cvt_pk_bf16_f32 v91, v92, v93
	global_store_dwordx2 v232, v[90:91], s[82:83]
	s_waitcnt lgkmcnt(4)
	v_cvt_pk_bf16_f32 v94, v94, v95
	v_cvt_pk_bf16_f32 v95, v96, v97
	global_store_dwordx2 v233, v[94:95], s[82:83]
	s_waitcnt lgkmcnt(3)
	v_cvt_pk_bf16_f32 v66, v66, v67
	v_cvt_pk_bf16_f32 v67, v68, v69
	global_store_dwordx2 v234, v[66:67], s[82:83]
	s_waitcnt lgkmcnt(2)
	v_cvt_pk_bf16_f32 v70, v70, v71
	v_cvt_pk_bf16_f32 v71, v72, v73
	global_store_dwordx2 v235, v[70:71], s[82:83]
	s_waitcnt lgkmcnt(1)
	v_cvt_pk_bf16_f32 v74, v74, v75
	v_cvt_pk_bf16_f32 v75, v76, v77
	global_store_dwordx2 v236, v[74:75], s[82:83]
	s_waitcnt lgkmcnt(0)
	v_cvt_pk_bf16_f32 v78, v78, v79
	v_cvt_pk_bf16_f32 v79, v80, v81
	global_store_dwordx2 v237, v[78:79], s[82:83]
	ds_write_b128 v220, v[50:53]
	ds_write_b128 v220, v[54:57] offset:32
	ds_write_b128 v220, v[58:61] offset:64
	ds_write_b128 v220, v[62:65] offset:96
	ds_write_b128 v220, v[34:37] offset:128
	ds_write_b128 v220, v[38:41] offset:160
	ds_write_b128 v220, v[42:45] offset:192
	ds_write_b128 v220, v[46:49] offset:224
	v_add_u32_e32 v230, 0x10000, v222
	v_add_u32_e32 v231, 0x12000, v222
	v_add_u32_e32 v232, 0x14000, v222
	v_add_u32_e32 v233, 0x16000, v222
	v_add_u32_e32 v234, 0x18000, v222
	v_add_u32_e32 v235, 0x1a000, v222
	v_add_u32_e32 v236, 0x1c000, v222
	v_add_u32_e32 v237, 0x1e000, v222
	s_waitcnt lgkmcnt(0)
	ds_read_b128 v[50:53], v221
	ds_read_b128 v[54:57], v221 offset:1088
	ds_read_b128 v[58:61], v221 offset:2176
	ds_read_b128 v[62:65], v221 offset:3264
	ds_read_b128 v[34:37], v221 offset:4352
	ds_read_b128 v[38:41], v221 offset:5440
	ds_read_b128 v[42:45], v221 offset:6528
	ds_read_b128 v[46:49], v221 offset:7616
	s_waitcnt lgkmcnt(7)
	v_cvt_pk_bf16_f32 v50, v50, v51
	v_cvt_pk_bf16_f32 v51, v52, v53
	global_store_dwordx2 v230, v[50:51], s[82:83]
	s_waitcnt lgkmcnt(6)
	v_cvt_pk_bf16_f32 v54, v54, v55
	v_cvt_pk_bf16_f32 v55, v56, v57
	global_store_dwordx2 v231, v[54:55], s[82:83]
	s_waitcnt lgkmcnt(5)
	v_cvt_pk_bf16_f32 v58, v58, v59
	v_cvt_pk_bf16_f32 v59, v60, v61
	global_store_dwordx2 v232, v[58:59], s[82:83]
	s_waitcnt lgkmcnt(4)
	v_cvt_pk_bf16_f32 v62, v62, v63
	v_cvt_pk_bf16_f32 v63, v64, v65
	global_store_dwordx2 v233, v[62:63], s[82:83]
	s_waitcnt lgkmcnt(3)
	v_cvt_pk_bf16_f32 v34, v34, v35
	v_cvt_pk_bf16_f32 v35, v36, v37
	global_store_dwordx2 v234, v[34:35], s[82:83]
	s_waitcnt lgkmcnt(2)
	v_cvt_pk_bf16_f32 v38, v38, v39
	v_cvt_pk_bf16_f32 v39, v40, v41
	global_store_dwordx2 v235, v[38:39], s[82:83]
	s_waitcnt lgkmcnt(1)
	v_cvt_pk_bf16_f32 v42, v42, v43
	v_cvt_pk_bf16_f32 v43, v44, v45
	global_store_dwordx2 v236, v[42:43], s[82:83]
	s_waitcnt lgkmcnt(0)
	v_cvt_pk_bf16_f32 v46, v46, v47
	v_cvt_pk_bf16_f32 v47, v48, v49
	global_store_dwordx2 v237, v[46:47], s[82:83]
	ds_write_b128 v220, v[18:21]
	ds_write_b128 v220, v[22:25] offset:32
	ds_write_b128 v220, v[26:29] offset:64
	ds_write_b128 v220, v[30:33] offset:96
	ds_write_b128 v220, v[2:5] offset:128
	ds_write_b128 v220, v[6:9] offset:160
	ds_write_b128 v220, v[10:13] offset:192
	ds_write_b128 v220, v[14:17] offset:224
	v_add_u32_e32 v230, 0x20000, v222
	v_add_u32_e32 v231, 0x22000, v222
	v_add_u32_e32 v232, 0x24000, v222
	v_add_u32_e32 v233, 0x26000, v222
	v_add_u32_e32 v234, 0x28000, v222
	v_add_u32_e32 v235, 0x2a000, v222
	v_add_u32_e32 v236, 0x2c000, v222
	v_add_u32_e32 v237, 0x2e000, v222
	s_waitcnt lgkmcnt(0)
	ds_read_b128 v[18:21], v221
	ds_read_b128 v[22:25], v221 offset:1088
	ds_read_b128 v[26:29], v221 offset:2176
	ds_read_b128 v[30:33], v221 offset:3264
	ds_read_b128 v[2:5], v221 offset:4352
	ds_read_b128 v[6:9], v221 offset:5440
	ds_read_b128 v[10:13], v221 offset:6528
	ds_read_b128 v[14:17], v221 offset:7616
	s_waitcnt lgkmcnt(7)
	v_cvt_pk_bf16_f32 v18, v18, v19
	v_cvt_pk_bf16_f32 v19, v20, v21
	global_store_dwordx2 v230, v[18:19], s[82:83]
	s_waitcnt lgkmcnt(6)
	v_cvt_pk_bf16_f32 v22, v22, v23
	v_cvt_pk_bf16_f32 v23, v24, v25
	global_store_dwordx2 v231, v[22:23], s[82:83]
	s_waitcnt lgkmcnt(5)
	v_cvt_pk_bf16_f32 v26, v26, v27
	v_cvt_pk_bf16_f32 v27, v28, v29
	global_store_dwordx2 v232, v[26:27], s[82:83]
	s_waitcnt lgkmcnt(4)
	v_cvt_pk_bf16_f32 v30, v30, v31
	v_cvt_pk_bf16_f32 v31, v32, v33
	global_store_dwordx2 v233, v[30:31], s[82:83]
	s_waitcnt lgkmcnt(3)
	v_cvt_pk_bf16_f32 v2, v2, v3
	v_cvt_pk_bf16_f32 v3, v4, v5
	global_store_dwordx2 v234, v[2:3], s[82:83]
	s_waitcnt lgkmcnt(2)
	v_cvt_pk_bf16_f32 v6, v6, v7
	v_cvt_pk_bf16_f32 v7, v8, v9
	global_store_dwordx2 v235, v[6:7], s[82:83]
	s_waitcnt lgkmcnt(1)
	v_cvt_pk_bf16_f32 v10, v10, v11
	v_cvt_pk_bf16_f32 v11, v12, v13
	global_store_dwordx2 v236, v[10:11], s[82:83]
	s_waitcnt lgkmcnt(0)
	v_cvt_pk_bf16_f32 v14, v14, v15
	v_cvt_pk_bf16_f32 v15, v16, v17
	global_store_dwordx2 v237, v[14:15], s[82:83]
	s_barrier
	s_branch .LBB0_1266
G1E_ph13_U:
	s_load_dwordx2 s[82:83], s[0:1], 0x160
	v_and_b32_e32 v223, 31, v0
	v_mul_u32_u24_e32 v220, 0x110, v223
	v_bfe_u32 v223, v0, 5, 1
	v_lshl_add_u32 v220, v223, 4, v220
	v_bfe_u32 v224, v0, 6, 2
	v_mul_u32_u24_e32 v223, 0x2200, v224
	v_add_u32_e32 v220, v220, v223
	v_bfe_u32 v222, v0, 4, 2
	v_mul_u32_u24_e32 v221, 0x110, v222
	v_add_u32_e32 v221, v221, v223
	v_and_b32_e32 v223, 15, v0
	v_lshl_add_u32 v221, v223, 4, v221
	s_lshr_b32 s85, s64, 6
	s_lshl_b32 s85, s85, 8
	s_and_b32 s84, s64, 63
	s_mulk_i32 s84, 0xc0
	v_lshrrev_b32_e32 v224, 1, v224
	v_mul_u32_u24_e32 v224, 0x60, v224
	v_add3_u32 v222, v222, v224, s84
	v_lshlrev_b32_e32 v222, 11, v222
	v_lshl_add_u32 v222, v223, 3, v222
	v_bfe_u32 v223, v0, 6, 1
	v_lshl_add_u32 v222, v223, 7, v222
	v_add_u32_e32 v222, s85, v222
	ds_write_b128 v220, v[82:85]
	ds_write_b128 v220, v[86:89] offset:32
	ds_write_b128 v220, v[90:93] offset:64
	ds_write_b128 v220, v[94:97] offset:96
	ds_write_b128 v220, v[66:69] offset:128
	ds_write_b128 v220, v[70:73] offset:160
	ds_write_b128 v220, v[74:77] offset:192
	ds_write_b128 v220, v[78:81] offset:224
	v_mov_b32_e32 v230, v222
	v_add_u32_e32 v231, 0x2000, v222
	v_add_u32_e32 v232, 0x4000, v222
	v_add_u32_e32 v233, 0x6000, v222
	v_add_u32_e32 v234, 0x8000, v222
	v_add_u32_e32 v235, 0xa000, v222
	v_add_u32_e32 v236, 0xc000, v222
	v_add_u32_e32 v237, 0xe000, v222
	s_waitcnt lgkmcnt(0)
	ds_read_b128 v[82:85], v221
	ds_read_b128 v[86:89], v221 offset:1088
	ds_read_b128 v[90:93], v221 offset:2176
	ds_read_b128 v[94:97], v221 offset:3264
	ds_read_b128 v[66:69], v221 offset:4352
	ds_read_b128 v[70:73], v221 offset:5440
	ds_read_b128 v[74:77], v221 offset:6528
	ds_read_b128 v[78:81], v221 offset:7616
	s_waitcnt lgkmcnt(7)
	v_mul_f32_e32 v82, 0x3e38aa3b, v82
	v_mul_f32_e32 v83, 0x3e38aa3b, v83
	v_mul_f32_e32 v84, 0x3e38aa3b, v84
	v_mul_f32_e32 v85, 0x3e38aa3b, v85
	v_cvt_pk_bf16_f32 v82, v82, v83
	v_cvt_pk_bf16_f32 v83, v84, v85
	global_store_dwordx2 v230, v[82:83], s[82:83]
	s_waitcnt lgkmcnt(6)
	v_mul_f32_e32 v86, 0x3e38aa3b, v86
	v_mul_f32_e32 v87, 0x3e38aa3b, v87
	v_mul_f32_e32 v88, 0x3e38aa3b, v88
	v_mul_f32_e32 v89, 0x3e38aa3b, v89
	v_cvt_pk_bf16_f32 v86, v86, v87
	v_cvt_pk_bf16_f32 v87, v88, v89
	global_store_dwordx2 v231, v[86:87], s[82:83]
	s_waitcnt lgkmcnt(5)
	v_mul_f32_e32 v90, 0x3e38aa3b, v90
	v_mul_f32_e32 v91, 0x3e38aa3b, v91
	v_mul_f32_e32 v92, 0x3e38aa3b, v92
	v_mul_f32_e32 v93, 0x3e38aa3b, v93
	v_cvt_pk_bf16_f32 v90, v90, v91
	v_cvt_pk_bf16_f32 v91, v92, v93
	global_store_dwordx2 v232, v[90:91], s[82:83]
	s_waitcnt lgkmcnt(4)
	v_mul_f32_e32 v94, 0x3e38aa3b, v94
	v_mul_f32_e32 v95, 0x3e38aa3b, v95
	v_mul_f32_e32 v96, 0x3e38aa3b, v96
	v_mul_f32_e32 v97, 0x3e38aa3b, v97
	v_cvt_pk_bf16_f32 v94, v94, v95
	v_cvt_pk_bf16_f32 v95, v96, v97
	global_store_dwordx2 v233, v[94:95], s[82:83]
	s_waitcnt lgkmcnt(3)
	v_mul_f32_e32 v66, 0x3e38aa3b, v66
	v_mul_f32_e32 v67, 0x3e38aa3b, v67
	v_mul_f32_e32 v68, 0x3e38aa3b, v68
	v_mul_f32_e32 v69, 0x3e38aa3b, v69
	v_cvt_pk_bf16_f32 v66, v66, v67
	v_cvt_pk_bf16_f32 v67, v68, v69
	global_store_dwordx2 v234, v[66:67], s[82:83]
	s_waitcnt lgkmcnt(2)
	v_mul_f32_e32 v70, 0x3e38aa3b, v70
	v_mul_f32_e32 v71, 0x3e38aa3b, v71
	v_mul_f32_e32 v72, 0x3e38aa3b, v72
	v_mul_f32_e32 v73, 0x3e38aa3b, v73
	v_cvt_pk_bf16_f32 v70, v70, v71
	v_cvt_pk_bf16_f32 v71, v72, v73
	global_store_dwordx2 v235, v[70:71], s[82:83]
	s_waitcnt lgkmcnt(1)
	v_mul_f32_e32 v74, 0x3e38aa3b, v74
	v_mul_f32_e32 v75, 0x3e38aa3b, v75
	v_mul_f32_e32 v76, 0x3e38aa3b, v76
	v_mul_f32_e32 v77, 0x3e38aa3b, v77
	v_cvt_pk_bf16_f32 v74, v74, v75
	v_cvt_pk_bf16_f32 v75, v76, v77
	global_store_dwordx2 v236, v[74:75], s[82:83]
	s_waitcnt lgkmcnt(0)
	v_mul_f32_e32 v78, 0x3e38aa3b, v78
	v_mul_f32_e32 v79, 0x3e38aa3b, v79
	v_mul_f32_e32 v80, 0x3e38aa3b, v80
	v_mul_f32_e32 v81, 0x3e38aa3b, v81
	v_cvt_pk_bf16_f32 v78, v78, v79
	v_cvt_pk_bf16_f32 v79, v80, v81
	global_store_dwordx2 v237, v[78:79], s[82:83]
	ds_write_b128 v220, v[50:53]
	ds_write_b128 v220, v[54:57] offset:32
	ds_write_b128 v220, v[58:61] offset:64
	ds_write_b128 v220, v[62:65] offset:96
	ds_write_b128 v220, v[34:37] offset:128
	ds_write_b128 v220, v[38:41] offset:160
	ds_write_b128 v220, v[42:45] offset:192
	ds_write_b128 v220, v[46:49] offset:224
	v_add_u32_e32 v230, 0x10000, v222
	v_add_u32_e32 v231, 0x12000, v222
	v_add_u32_e32 v232, 0x14000, v222
	v_add_u32_e32 v233, 0x16000, v222
	v_add_u32_e32 v234, 0x18000, v222
	v_add_u32_e32 v235, 0x1a000, v222
	v_add_u32_e32 v236, 0x1c000, v222
	v_add_u32_e32 v237, 0x1e000, v222
	s_waitcnt lgkmcnt(0)
	ds_read_b128 v[50:53], v221
	ds_read_b128 v[54:57], v221 offset:1088
	ds_read_b128 v[58:61], v221 offset:2176
	ds_read_b128 v[62:65], v221 offset:3264
	ds_read_b128 v[34:37], v221 offset:4352
	ds_read_b128 v[38:41], v221 offset:5440
	ds_read_b128 v[42:45], v221 offset:6528
	ds_read_b128 v[46:49], v221 offset:7616
	s_waitcnt lgkmcnt(7)
	v_mul_f32_e32 v50, 0x3e38aa3b, v50
	v_mul_f32_e32 v51, 0x3e38aa3b, v51
	v_mul_f32_e32 v52, 0x3e38aa3b, v52
	v_mul_f32_e32 v53, 0x3e38aa3b, v53
	v_cvt_pk_bf16_f32 v50, v50, v51
	v_cvt_pk_bf16_f32 v51, v52, v53
	global_store_dwordx2 v230, v[50:51], s[82:83]
	s_waitcnt lgkmcnt(6)
	v_mul_f32_e32 v54, 0x3e38aa3b, v54
	v_mul_f32_e32 v55, 0x3e38aa3b, v55
	v_mul_f32_e32 v56, 0x3e38aa3b, v56
	v_mul_f32_e32 v57, 0x3e38aa3b, v57
	v_cvt_pk_bf16_f32 v54, v54, v55
	v_cvt_pk_bf16_f32 v55, v56, v57
	global_store_dwordx2 v231, v[54:55], s[82:83]
	s_waitcnt lgkmcnt(5)
	v_mul_f32_e32 v58, 0x3e38aa3b, v58
	v_mul_f32_e32 v59, 0x3e38aa3b, v59
	v_mul_f32_e32 v60, 0x3e38aa3b, v60
	v_mul_f32_e32 v61, 0x3e38aa3b, v61
	v_cvt_pk_bf16_f32 v58, v58, v59
	v_cvt_pk_bf16_f32 v59, v60, v61
	global_store_dwordx2 v232, v[58:59], s[82:83]
	s_waitcnt lgkmcnt(4)
	v_mul_f32_e32 v62, 0x3e38aa3b, v62
	v_mul_f32_e32 v63, 0x3e38aa3b, v63
	v_mul_f32_e32 v64, 0x3e38aa3b, v64
	v_mul_f32_e32 v65, 0x3e38aa3b, v65
	v_cvt_pk_bf16_f32 v62, v62, v63
	v_cvt_pk_bf16_f32 v63, v64, v65
	global_store_dwordx2 v233, v[62:63], s[82:83]
	s_waitcnt lgkmcnt(3)
	v_mul_f32_e32 v34, 0x3e38aa3b, v34
	v_mul_f32_e32 v35, 0x3e38aa3b, v35
	v_mul_f32_e32 v36, 0x3e38aa3b, v36
	v_mul_f32_e32 v37, 0x3e38aa3b, v37
	v_cvt_pk_bf16_f32 v34, v34, v35
	v_cvt_pk_bf16_f32 v35, v36, v37
	global_store_dwordx2 v234, v[34:35], s[82:83]
	s_waitcnt lgkmcnt(2)
	v_mul_f32_e32 v38, 0x3e38aa3b, v38
	v_mul_f32_e32 v39, 0x3e38aa3b, v39
	v_mul_f32_e32 v40, 0x3e38aa3b, v40
	v_mul_f32_e32 v41, 0x3e38aa3b, v41
	v_cvt_pk_bf16_f32 v38, v38, v39
	v_cvt_pk_bf16_f32 v39, v40, v41
	global_store_dwordx2 v235, v[38:39], s[82:83]
	s_waitcnt lgkmcnt(1)
	v_mul_f32_e32 v42, 0x3e38aa3b, v42
	v_mul_f32_e32 v43, 0x3e38aa3b, v43
	v_mul_f32_e32 v44, 0x3e38aa3b, v44
	v_mul_f32_e32 v45, 0x3e38aa3b, v45
	v_cvt_pk_bf16_f32 v42, v42, v43
	v_cvt_pk_bf16_f32 v43, v44, v45
	global_store_dwordx2 v236, v[42:43], s[82:83]
	s_waitcnt lgkmcnt(0)
	v_mul_f32_e32 v46, 0x3e38aa3b, v46
	v_mul_f32_e32 v47, 0x3e38aa3b, v47
	v_mul_f32_e32 v48, 0x3e38aa3b, v48
	v_mul_f32_e32 v49, 0x3e38aa3b, v49
	v_cvt_pk_bf16_f32 v46, v46, v47
	v_cvt_pk_bf16_f32 v47, v48, v49
	global_store_dwordx2 v237, v[46:47], s[82:83]
	ds_write_b128 v220, v[18:21]
	ds_write_b128 v220, v[22:25] offset:32
	ds_write_b128 v220, v[26:29] offset:64
	ds_write_b128 v220, v[30:33] offset:96
	ds_write_b128 v220, v[2:5] offset:128
	ds_write_b128 v220, v[6:9] offset:160
	ds_write_b128 v220, v[10:13] offset:192
	ds_write_b128 v220, v[14:17] offset:224
	v_add_u32_e32 v230, 0x20000, v222
	v_add_u32_e32 v231, 0x22000, v222
	v_add_u32_e32 v232, 0x24000, v222
	v_add_u32_e32 v233, 0x26000, v222
	v_add_u32_e32 v234, 0x28000, v222
	v_add_u32_e32 v235, 0x2a000, v222
	v_add_u32_e32 v236, 0x2c000, v222
	v_add_u32_e32 v237, 0x2e000, v222
	s_waitcnt lgkmcnt(0)
	ds_read_b128 v[18:21], v221
	ds_read_b128 v[22:25], v221 offset:1088
	ds_read_b128 v[26:29], v221 offset:2176
	ds_read_b128 v[30:33], v221 offset:3264
	ds_read_b128 v[2:5], v221 offset:4352
	ds_read_b128 v[6:9], v221 offset:5440
	ds_read_b128 v[10:13], v221 offset:6528
	ds_read_b128 v[14:17], v221 offset:7616
	s_waitcnt lgkmcnt(7)
	v_mul_f32_e32 v18, 0x3e38aa3b, v18
	v_mul_f32_e32 v19, 0x3e38aa3b, v19
	v_mul_f32_e32 v20, 0x3e38aa3b, v20
	v_mul_f32_e32 v21, 0x3e38aa3b, v21
	v_cvt_pk_bf16_f32 v18, v18, v19
	v_cvt_pk_bf16_f32 v19, v20, v21
	global_store_dwordx2 v230, v[18:19], s[82:83]
	s_waitcnt lgkmcnt(6)
	v_mul_f32_e32 v22, 0x3e38aa3b, v22
	v_mul_f32_e32 v23, 0x3e38aa3b, v23
	v_mul_f32_e32 v24, 0x3e38aa3b, v24
	v_mul_f32_e32 v25, 0x3e38aa3b, v25
	v_cvt_pk_bf16_f32 v22, v22, v23
	v_cvt_pk_bf16_f32 v23, v24, v25
	global_store_dwordx2 v231, v[22:23], s[82:83]
	s_waitcnt lgkmcnt(5)
	v_mul_f32_e32 v26, 0x3e38aa3b, v26
	v_mul_f32_e32 v27, 0x3e38aa3b, v27
	v_mul_f32_e32 v28, 0x3e38aa3b, v28
	v_mul_f32_e32 v29, 0x3e38aa3b, v29
	v_cvt_pk_bf16_f32 v26, v26, v27
	v_cvt_pk_bf16_f32 v27, v28, v29
	global_store_dwordx2 v232, v[26:27], s[82:83]
	s_waitcnt lgkmcnt(4)
	v_mul_f32_e32 v30, 0x3e38aa3b, v30
	v_mul_f32_e32 v31, 0x3e38aa3b, v31
	v_mul_f32_e32 v32, 0x3e38aa3b, v32
	v_mul_f32_e32 v33, 0x3e38aa3b, v33
	v_cvt_pk_bf16_f32 v30, v30, v31
	v_cvt_pk_bf16_f32 v31, v32, v33
	global_store_dwordx2 v233, v[30:31], s[82:83]
	s_waitcnt lgkmcnt(3)
	v_mul_f32_e32 v2, 0x3e38aa3b, v2
	v_mul_f32_e32 v3, 0x3e38aa3b, v3
	v_mul_f32_e32 v4, 0x3e38aa3b, v4
	v_mul_f32_e32 v5, 0x3e38aa3b, v5
	v_cvt_pk_bf16_f32 v2, v2, v3
	v_cvt_pk_bf16_f32 v3, v4, v5
	global_store_dwordx2 v234, v[2:3], s[82:83]
	s_waitcnt lgkmcnt(2)
	v_mul_f32_e32 v6, 0x3e38aa3b, v6
	v_mul_f32_e32 v7, 0x3e38aa3b, v7
	v_mul_f32_e32 v8, 0x3e38aa3b, v8
	v_mul_f32_e32 v9, 0x3e38aa3b, v9
	v_cvt_pk_bf16_f32 v6, v6, v7
	v_cvt_pk_bf16_f32 v7, v8, v9
	global_store_dwordx2 v235, v[6:7], s[82:83]
	s_waitcnt lgkmcnt(1)
	v_mul_f32_e32 v10, 0x3e38aa3b, v10
	v_mul_f32_e32 v11, 0x3e38aa3b, v11
	v_mul_f32_e32 v12, 0x3e38aa3b, v12
	v_mul_f32_e32 v13, 0x3e38aa3b, v13
	v_cvt_pk_bf16_f32 v10, v10, v11
	v_cvt_pk_bf16_f32 v11, v12, v13
	global_store_dwordx2 v236, v[10:11], s[82:83]
	s_waitcnt lgkmcnt(0)
	v_mul_f32_e32 v14, 0x3e38aa3b, v14
	v_mul_f32_e32 v15, 0x3e38aa3b, v15
	v_mul_f32_e32 v16, 0x3e38aa3b, v16
	v_mul_f32_e32 v17, 0x3e38aa3b, v17
	v_cvt_pk_bf16_f32 v14, v14, v15
	v_cvt_pk_bf16_f32 v15, v16, v17
	global_store_dwordx2 v237, v[14:15], s[82:83]
	s_barrier
	s_branch .LBB0_1266
G1E_ph13_ORIG:
	s_and_b32 s5, s5, 0x1fffff8
	s_nop 4
	s_cmp_eq_u32 s5, 16
	s_nop 4
	s_cselect_b64 s[50:51], -1, 0
	s_nop 4
	s_cmpk_gt_u32 s4, 0x7ff
	s_nop 4
	s_cselect_b64 s[48:49], -1, 0
	s_nop 4
	s_cmpk_gt_u32 s4, 0xbff
	s_nop 4
	s_cselect_b64 s[46:47], -1, 0
	s_nop 4
	s_mov_b64 s[52:53], -1
	s_nop 4
	s_and_b64 vcc, exec, s[50:51]
	s_nop 4
	v_add_u32_e32 v109, s6, v119
	s_nop 4
	v_or_b32_e32 v100, s4, v127
	s_waitcnt lgkmcnt(0)
	s_nop 11
	ds_write_b128 v140, v[82:85]
	ds_write_b128 v140, v[86:89] offset:32
	ds_write_b128 v140, v[90:93] offset:64
	ds_write_b128 v140, v[94:97] offset:96
	s_nop 11
	ds_write_b128 v140, v[66:69] offset:128
	ds_write_b128 v140, v[70:73] offset:160
	ds_write_b128 v140, v[74:77] offset:192
	ds_write_b128 v140, v[78:81] offset:224
	s_waitcnt lgkmcnt(0)
	v_add_u32_e32 v112, v128, v100
	v_or_b32_e32 v100, v100, v131
	v_cmp_lt_i32_e64 s[6:7], s3, v100
	s_cbranch_vccz .LBB0_1278
	v_mov_b32_e32 v80, 0x880
	v_cmp_gt_i32_e64 s[52:53], s57, v109
	v_mov_b32_e32 v81, 0x990
	v_mov_b32_e32 v79, 0xaa0
	v_mov_b32_e32 v78, 0xbb0
	ds_read2_b32 v[70:71], v129 offset1:68
	ds_read2_b32 v[72:73], v129 offset0:136 offset1:204
	v_cndmask_b32_e64 v82, v141, v80, s[52:53]
	v_cndmask_b32_e64 v83, v142, v81, s[52:53]
	v_cndmask_b32_e64 v84, v143, v79, s[52:53]
	v_cndmask_b32_e64 v85, v144, v78, s[52:53]
	v_add_u32_e32 v66, 0xfffff000, v109
	v_ashrrev_i32_e32 v68, 8, v109
	v_add_u32_e32 v82, v129, v82
	v_add_u32_e32 v83, v129, v83
	v_add_u32_e32 v84, v129, v84
	v_add_u32_e32 v85, v129, v85
	v_lshrrev_b32_e32 v66, 11, v66
	v_and_b32_e32 v67, 0x7e0, v109
	v_ashrrev_i32_e32 v69, 31, v68
	ds_read_b32 v82, v82
	ds_read_b32 v83, v83
	ds_read_b32 v84, v84
	ds_read_b32 v85, v85
	v_add_u32_e32 v76, 0x100, v67
	v_mad_u64_u32 v[66:67], s[4:5], v66, s59, v[110:111]
	v_lshlrev_b64 v[68:69], 18, v[68:69]
	v_and_b32_e32 v77, 0xe0, v109
	v_cndmask_b32_e64 v75, v67, v69, s[52:53]
	v_cndmask_b32_e64 v74, v66, v68, s[52:53]
	v_cndmask_b32_e64 v86, v145, v147, s[52:53]
	v_cndmask_b32_e64 v87, v76, v77, s[52:53]
	s_waitcnt lgkmcnt(0)
	v_cvt_pk_bf16_f32 v70, v70, v71
	v_cvt_pk_bf16_f32 v71, v72, v73
	v_cvt_pk_bf16_f32 v72, v82, v83
	v_lshl_add_u64 v[74:75], v[74:75], 1, s[24:25]
	v_mad_u64_u32 v[82:83], s[4:5], v86, v112, 0
	v_lshl_add_u64 v[74:75], v[82:83], 1, v[74:75]
	v_lshlrev_b32_e32 v82, 1, v87
	v_mov_b32_e32 v83, v101
	v_cvt_pk_bf16_f32 v73, v84, v85
	v_lshl_add_u64 v[74:75], v[74:75], 0, v[82:83]
	global_store_dwordx4 v[74:75], v[70:73], off
	v_mov_b32_e32 v84, 0x1540
	v_mov_b32_e32 v83, 0x1650
	v_mov_b64_e32 v[70:71], 0x900
	v_mov_b64_e32 v[72:73], 0x900
	v_mov_b32_e32 v82, 0x1760
	v_mov_b32_e32 v71, 0x1870
	v_mov_b64_e32 v[74:75], v[66:67]
	v_mov_b32_e32 v73, v76
	s_and_saveexec_b64 s[4:5], s[52:53]
	s_cbranch_execz .LBB0_1275
	v_mov_b64_e32 v[72:73], 0x100
	v_mov_b32_e32 v78, 0x770
	v_mov_b32_e32 v79, 0x660
	v_mov_b32_e32 v81, 0x550
	v_mov_b32_e32 v80, 0x440
	v_mov_b32_e32 v84, 0x1980
	v_mov_b32_e32 v83, 0x1a90
	v_mov_b32_e32 v82, 0x1ba0
	v_mov_b32_e32 v71, 0x1cb0
	v_mov_b64_e32 v[74:75], v[68:69]
	v_mov_b32_e32 v73, v77
